# combined input projection on chunk-major H (norm1) and W_in: own operand addressing in the main K loop, re-based pointers in the 64-row remainder tiles
# baseline (speedup 1.0000x reference)
.LBB0_276:
	v_mov_b32_e32 v0, v142
	v_mov_b32_e32 v2, v142
	s_lshl_b32 s2, s17, 8
	v_lshlrev_b32_e32 v5, 7, v2
	v_lshlrev_b32_e32 v4, 6, v2
	v_and_b32_e32 v31, 0x2000, v5
	v_lshlrev_b32_e32 v5, 2, v2
	v_and_b32_e32 v3, 48, v2
	v_and_b32_e32 v30, 0xffffe000, v4
	v_and_b32_e32 v4, 0x3c0, v4
	v_and_b32_e32 v5, 32, v5
	v_bitop3_b32 v32, v4, v5, v3 bitop3:0x36
	v_ashrrev_i32_e32 v3, 31, v2
	v_lshrrev_b32_e32 v3, 26, v3
	v_lshlrev_b32_e32 v33, 4, v2
	v_add_u32_e32 v3, v2, v3
	v_bfe_i32 v2, v2, 27, 1
	v_lshrrev_b32_e32 v2, 22, v2
	v_add_u32_e32 v2, v33, v2
	v_and_b32_e32 v2, 0xfffffc00, v2
	v_sub_u32_e32 v2, v33, v2
	v_lshrrev_b32_e32 v4, 4, v2
	v_bitop3_b32 v4, v4, v2, 32 bitop3:0x6c
	v_ashrrev_i32_e32 v2, 31, v2
	v_ashrrev_i32_e32 v3, 6, v3
	v_lshrrev_b32_e32 v2, 26, v2
	v_lshlrev_b32_e32 v5, 3, v3
	v_add_u32_e32 v2, v4, v2
	v_and_b32_e32 v5, -16, v5
	v_ashrrev_i32_e32 v6, 6, v2
	v_add_u32_e32 v2, v6, v5
	v_mul_i32_i24_e32 v5, 64, v6
	s_ashr_i32 s3, s2, 31
	v_lshlrev_b32_e32 v3, 5, v3
	v_sub_u32_e32 v4, v4, v5
	s_lshl_b32 s40, s18, 7
	s_lshl_b64 s[4:5], s[2:3], 11
	v_and_b32_e32 v3, 32, v3
	v_ashrrev_i16_sdwa v4, v146, sext(v4) dst_sel:DWORD dst_unused:UNUSED_PAD src0_sel:DWORD src1_sel:BYTE_0
	s_add_u32 s10, s24, s4
	v_add_u32_sdwa v4, v3, sext(v4) dst_sel:DWORD dst_unused:UNUSED_PAD src0_sel:DWORD src1_sel:WORD_0
	v_ashrrev_i32_e32 v3, 31, v2
	s_addc_u32 s11, s25, s5
	v_lshlrev_b64 v[2:3], 11, v[2:3]
	v_ashrrev_i32_e32 v5, 31, v4
	v_add_u32_e32 v78, 0, v33
	v_add_u32_e32 v34, 0x2000, v33
	v_lshl_add_u64 v[6:7], s[10:11], 0, v[2:3]
	v_lshlrev_b64 v[4:5], 1, v[4:5]
	v_readfirstlane_b32 s19, v78
	v_ashrrev_i32_e32 v8, 31, v34
	v_add_u32_e32 v14, 0x2000, v78
	v_add_u32_e32 v35, 0x4000, v33
	v_lshl_add_u64 v[6:7], v[6:7], 0, v[4:5]
	s_mov_b32 m0, s19
	v_lshrrev_b32_e32 v8, 22, v8
	v_readfirstlane_b32 s19, v14
	v_ashrrev_i32_e32 v14, 31, v35
	v_add_u32_e32 v20, 0x4000, v78
	v_add_u32_e32 v36, 0x6000, v33
	s_waitcnt vmcnt(0) lgkmcnt(0)
	s_barrier
	v_add_u32_e32 v8, v34, v8
	s_mov_b32 m0, s19
	v_lshrrev_b32_e32 v14, 22, v14
	v_readfirstlane_b32 s19, v20
	v_ashrrev_i32_e32 v20, 31, v36
	v_ashrrev_i32_e32 v9, 10, v8
	v_add_u32_e32 v14, v35, v14
	v_lshrrev_b32_e32 v20, 22, v20
	v_mul_i32_i24_e32 v8, 0x400, v9
	v_ashrrev_i32_e32 v15, 10, v14
	v_add_u32_e32 v20, v36, v20
	v_sub_u32_e32 v8, v34, v8
	v_mul_i32_i24_e32 v14, 0x400, v15
	v_ashrrev_i32_e32 v21, 10, v20
	v_lshrrev_b32_e32 v10, 4, v8
	v_sub_u32_e32 v14, v35, v14
	v_mul_i32_i24_e32 v20, 0x400, v21
	v_bitop3_b32 v10, v10, v8, 32 bitop3:0x6c
	v_lshrrev_b32_e32 v16, 4, v14
	v_sub_u32_e32 v20, v36, v20
	v_ashrrev_i32_e32 v11, 31, v10
	v_bitop3_b32 v16, v16, v14, 32 bitop3:0x6c
	v_lshrrev_b32_e32 v22, 4, v20
	v_lshrrev_b32_e32 v11, 26, v11
	v_ashrrev_i32_e32 v17, 31, v16
	v_bitop3_b32 v22, v22, v20, 32 bitop3:0x6c
	v_add_u32_e32 v11, v10, v11
	v_lshrrev_b32_e32 v17, 26, v17
	v_ashrrev_i32_e32 v23, 31, v22
	v_lshlrev_b32_e32 v8, 3, v9
	v_ashrrev_i32_e32 v12, 6, v11
	v_and_b32_e32 v11, 0xc0, v11
	v_add_u32_e32 v17, v16, v17
	v_lshrrev_b32_e32 v23, 26, v23
	v_and_b32_e32 v8, -16, v8
	v_lshlrev_b32_e32 v9, 5, v9
	v_sub_u32_e32 v10, v10, v11
	v_lshlrev_b32_e32 v14, 3, v15
	v_ashrrev_i32_e32 v18, 6, v17
	v_and_b32_e32 v17, 0xc0, v17
	v_add_u32_e32 v23, v22, v23
	v_add_u32_e32 v8, v12, v8
	v_and_b32_e32 v9, 32, v9
	v_ashrrev_i16_sdwa v10, v146, sext(v10) dst_sel:DWORD dst_unused:UNUSED_PAD src0_sel:DWORD src1_sel:BYTE_0
	v_and_b32_e32 v14, -16, v14
	v_lshlrev_b32_e32 v15, 5, v15
	v_sub_u32_e32 v16, v16, v17
	v_lshlrev_b32_e32 v20, 3, v21
	v_ashrrev_i32_e32 v24, 6, v23
	v_and_b32_e32 v23, 0xc0, v23
	v_add_u32_sdwa v10, v9, sext(v10) dst_sel:DWORD dst_unused:UNUSED_PAD src0_sel:DWORD src1_sel:WORD_0
	v_ashrrev_i32_e32 v9, 31, v8
	v_add_u32_e32 v14, v18, v14
	v_and_b32_e32 v15, 32, v15
	v_ashrrev_i16_sdwa v16, v146, sext(v16) dst_sel:DWORD dst_unused:UNUSED_PAD src0_sel:DWORD src1_sel:BYTE_0
	v_and_b32_e32 v20, -16, v20
	v_lshlrev_b32_e32 v21, 5, v21
	v_sub_u32_e32 v22, v22, v23
	s_ashr_i32 s41, s40, 31
	v_lshlrev_b64 v[8:9], 11, v[8:9]
	v_ashrrev_i32_e32 v11, 31, v10
	v_add_u32_sdwa v16, v15, sext(v16) dst_sel:DWORD dst_unused:UNUSED_PAD src0_sel:DWORD src1_sel:WORD_0
	v_ashrrev_i32_e32 v15, 31, v14
	v_add_u32_e32 v20, v24, v20
	v_and_b32_e32 v21, 32, v21
	v_ashrrev_i16_sdwa v22, v146, sext(v22) dst_sel:DWORD dst_unused:UNUSED_PAD src0_sel:DWORD src1_sel:BYTE_0
	s_lshl_b64 s[6:7], s[40:41], 11
	v_lshl_add_u64 v[12:13], s[10:11], 0, v[8:9]
	v_lshlrev_b64 v[10:11], 1, v[10:11]
	v_lshlrev_b64 v[14:15], 11, v[14:15]
	v_ashrrev_i32_e32 v17, 31, v16
	v_add_u32_sdwa v22, v21, sext(v22) dst_sel:DWORD dst_unused:UNUSED_PAD src0_sel:DWORD src1_sel:WORD_0
	v_ashrrev_i32_e32 v21, 31, v20
	s_add_u32 s8, s14, s6
	v_lshl_add_u64 v[12:13], v[12:13], 0, v[10:11]
	v_lshl_add_u64 v[18:19], s[10:11], 0, v[14:15]
	v_lshlrev_b64 v[16:17], 1, v[16:17]
	v_lshlrev_b64 v[20:21], 11, v[20:21]
	v_ashrrev_i32_e32 v23, 31, v22
	v_add_u32_e32 v26, 0x6000, v78
	s_addc_u32 s9, s15, s7
	v_lshl_add_u64 v[18:19], v[18:19], 0, v[16:17]
	s_mov_b32 m0, s19
	v_lshl_add_u64 v[24:25], s[10:11], 0, v[20:21]
	v_lshlrev_b64 v[22:23], 1, v[22:23]
	v_readfirstlane_b32 s10, v26
	v_add_u32_e32 v28, 0x8000, v78
	v_lshl_add_u64 v[24:25], v[24:25], 0, v[22:23]
	s_mov_b32 m0, s10
	v_lshl_add_u64 v[26:27], s[8:9], 0, v[2:3]
	v_readfirstlane_b32 s10, v28
	v_add_u32_e32 v37, 0xa000, v78
	v_lshl_add_u64 v[26:27], v[26:27], 0, v[4:5]
	s_mov_b32 m0, s10
	v_lshl_add_u64 v[28:29], s[8:9], 0, v[8:9]
	v_readfirstlane_b32 s8, v37
	v_add_u32_e32 v37, 0xc000, v78
	v_lshl_add_u64 v[28:29], v[28:29], 0, v[10:11]
	s_mov_b32 m0, s8
	v_readfirstlane_b32 s8, v37
	v_lshl_add_u64 v[6:7], v[6:7], 0, s[30:31]
	s_mov_b32 m0, s8
	s_mov_b32 s3, 2
	v_lshl_add_u64 v[6:7], v[12:13], 0, s[30:31]
	v_add_u32_e32 v12, 0xe000, v78
	v_add3_u32 v80, v30, 0, v32
	v_readfirstlane_b32 s8, v12
	s_mov_b32 m0, s8
	s_add_i32 s8, 0, 0xc000
	v_add_u32_e32 v12, s8, v35
	v_readfirstlane_b32 s9, v12
	v_add_u32_e32 v12, s8, v36
	v_lshl_add_u64 v[6:7], v[18:19], 0, s[30:31]
	s_mov_b32 m0, s9
	v_readfirstlane_b32 s8, v12
	v_add_u32_e32 v12, s54, v33
	v_lshl_add_u64 v[6:7], v[24:25], 0, s[30:31]
	s_mov_b32 m0, s8
	v_readfirstlane_b32 s8, v12
	v_add_u32_e32 v12, s54, v34
	v_lshl_add_u64 v[6:7], v[26:27], 0, s[30:31]
	s_mov_b32 m0, s8
	v_readfirstlane_b32 s8, v12
	v_lshl_add_u64 v[6:7], v[28:29], 0, s[30:31]
	s_mov_b32 m0, s8
	s_add_i32 s8, 0, 0x8000
	v_lshl_add_u64 v[6:7], s[6:7], 0, v[8:9]
	v_lshl_add_u64 v[6:7], v[6:7], 0, v[10:11]
	v_lshl_add_u64 v[66:67], s[0:1], 0, v[6:7]
	v_lshl_add_u64 v[6:7], s[6:7], 0, v[2:3]
	v_lshl_add_u64 v[6:7], v[6:7], 0, v[4:5]
	v_lshl_add_u64 v[68:69], s[0:1], 0, v[6:7]
	v_lshl_add_u64 v[6:7], s[4:5], 0, v[20:21]
	v_lshl_add_u64 v[6:7], v[6:7], 0, v[22:23]
	v_lshl_add_u64 v[70:71], s[90:91], 0, v[6:7]
	v_lshl_add_u64 v[6:7], s[4:5], 0, v[14:15]
	v_lshl_add_u64 v[6:7], v[6:7], 0, v[16:17]
	v_lshl_add_u64 v[2:3], s[4:5], 0, v[2:3]
	v_lshl_add_u64 v[72:73], s[90:91], 0, v[6:7]
	v_lshl_add_u64 v[6:7], s[4:5], 0, v[8:9]
	v_lshl_add_u64 v[2:3], v[2:3], 0, v[4:5]
	v_lshl_add_u64 v[6:7], v[6:7], 0, v[10:11]
	v_lshl_add_u64 v[76:77], s[90:91], 0, v[2:3]
	v_mov_b32_e32 v2, 0
	v_add3_u32 v79, v31, s8, v32
	v_lshl_add_u64 v[74:75], s[90:91], 0, v[6:7]
	s_mov_b32 s6, 0
	s_mov_b64 s[4:5], 0
	v_mov_b32_e32 v3, v2
	v_mov_b32_e32 v4, v2
	v_mov_b32_e32 v5, v2
	v_mov_b32_e32 v6, v2
	v_mov_b32_e32 v7, v2
	v_mov_b32_e32 v8, v2
	v_mov_b32_e32 v9, v2
	v_mov_b32_e32 v10, v2
	v_mov_b32_e32 v11, v2
	v_mov_b32_e32 v12, v2
	v_mov_b32_e32 v13, v2
	v_mov_b32_e32 v14, v2
	v_mov_b32_e32 v15, v2
	v_mov_b32_e32 v16, v2
	v_mov_b32_e32 v17, v2
	v_mov_b32_e32 v18, v2
	v_mov_b32_e32 v19, v2
	v_mov_b32_e32 v20, v2
	v_mov_b32_e32 v21, v2
	v_mov_b32_e32 v22, v2
	v_mov_b32_e32 v23, v2
	v_mov_b32_e32 v24, v2
	v_mov_b32_e32 v25, v2
	v_mov_b32_e32 v26, v2
	v_mov_b32_e32 v27, v2
	v_mov_b32_e32 v28, v2
	v_mov_b32_e32 v29, v2
	v_mov_b32_e32 v30, v2
	v_mov_b32_e32 v31, v2
	v_mov_b32_e32 v32, v2
	v_mov_b32_e32 v33, v2
	v_mov_b32_e32 v34, v2
	v_mov_b32_e32 v35, v2
	v_mov_b32_e32 v36, v2
	v_mov_b32_e32 v37, v2
	v_mov_b32_e32 v38, v2
	v_mov_b32_e32 v39, v2
	v_mov_b32_e32 v40, v2
	v_mov_b32_e32 v41, v2
	v_mov_b32_e32 v42, v2
	v_mov_b32_e32 v43, v2
	v_mov_b32_e32 v44, v2
	v_mov_b32_e32 v45, v2
	v_mov_b32_e32 v46, v2
	v_mov_b32_e32 v47, v2
	v_mov_b32_e32 v48, v2
	v_mov_b32_e32 v49, v2
	v_mov_b32_e32 v50, v2
	v_mov_b32_e32 v51, v2
	v_mov_b32_e32 v52, v2
	v_mov_b32_e32 v53, v2
	v_mov_b32_e32 v54, v2
	v_mov_b32_e32 v55, v2
	v_mov_b32_e32 v56, v2
	v_mov_b32_e32 v57, v2
	v_mov_b32_e32 v58, v2
	v_mov_b32_e32 v59, v2
	v_mov_b32_e32 v60, v2
	v_mov_b32_e32 v61, v2
	v_mov_b32_e32 v62, v2
	v_mov_b32_e32 v63, v2
	v_mov_b32_e32 v64, v2
	v_mov_b32_e32 v65, v2
.LBB0_277:
	s_lshl_b32 s38, s17, 19
	s_add_u32 s4, s24, s38
	s_addc_u32 s5, s25, 0
	s_lshl_b32 s38, s18, 18
	s_add_u32 s42, s14, s38
	s_addc_u32 s43, s15, 0
	v_and_b32_e32 v226, 63, v142
	v_lshlrev_b32_e32 v222, 4, v226
	v_lshrrev_b32_e32 v227, 5, v226
	v_lshlrev_b32_e32 v227, 5, v227
	v_xor_b32_e32 v222, v222, v227
	v_lshrrev_b32_e32 v226, 6, v142
	v_and_b32_e32 v227, 1, v226
	v_lshl_add_u32 v222, v227, 10, v222
	v_lshrrev_b32_e32 v226, 1, v226
	v_lshl_add_u32 v222, v226, 15, v222
	v_add_u32_e32 v223, 0x20000, v222
	v_add_u32_e32 v224, 0x20000, v223
	v_add_u32_e32 v225, 0x20000, v224
	v_add_u32_e32 v218, 0x0, v78
	s_nop 0
	v_readfirstlane_b32 s7, v218
	s_add_u32 m0, s7, 0x0
	s_nop 0
	global_load_lds_dwordx4 v222, s[4:5]
	s_add_u32 m0, s7, 0x2000
	s_nop 0
	global_load_lds_dwordx4 v223, s[4:5]
	s_add_u32 m0, s7, 0x4000
	s_nop 0
	global_load_lds_dwordx4 v224, s[4:5]
	s_add_u32 m0, s7, 0x6000
	s_nop 0
	global_load_lds_dwordx4 v225, s[4:5]
	s_add_u32 m0, s7, 0x8000
	s_nop 0
	global_load_lds_dwordx4 v222, s[42:43]
	s_add_u32 m0, s7, 0xa000
	s_nop 0
	global_load_lds_dwordx4 v223, s[42:43]
	s_add_u32 s4, s4, 0x800
	s_addc_u32 s5, s5, 0
	s_add_u32 s42, s42, 0x800
	s_addc_u32 s43, s43, 0
	v_add_u32_e32 v218, 0xc000, v78
	s_nop 0
	v_readfirstlane_b32 s7, v218
	s_add_u32 m0, s7, 0x0
	s_nop 0
	global_load_lds_dwordx4 v222, s[4:5]
	s_add_u32 m0, s7, 0x2000
	s_nop 0
	global_load_lds_dwordx4 v223, s[4:5]
	s_add_u32 m0, s7, 0x4000
	s_nop 0
	global_load_lds_dwordx4 v224, s[4:5]
	s_add_u32 m0, s7, 0x6000
	s_nop 0
	global_load_lds_dwordx4 v225, s[4:5]
	s_add_u32 m0, s7, 0x8000
	s_nop 0
	global_load_lds_dwordx4 v222, s[42:43]
	s_add_u32 m0, s7, 0xa000
	s_nop 0
	global_load_lds_dwordx4 v223, s[42:43]
	s_add_u32 s4, s4, 0x800
	s_addc_u32 s5, s5, 0
	s_add_u32 s42, s42, 0x800
	s_addc_u32 s43, s43, 0
	s_mov_b32 s32, 14
.Lgb_gwin:
	s_waitcnt vmcnt(6)
	s_barrier
	s_mul_i32 s7, s6, 0xc000
	v_add_u32_e32 v220, s7, v80
	v_add_u32_e32 v221, s7, v79
	ds_read_b128 v[82:85], v220 offset:0
	ds_read_b128 v[86:89], v220 offset:2048
	ds_read_b128 v[90:93], v220 offset:4096
	ds_read_b128 v[94:97], v220 offset:6144
	ds_read_b128 v[98:101], v221 offset:0
	ds_read_b128 v[102:105], v221 offset:2048
	ds_read_b128 v[106:109], v221 offset:4096
	ds_read_b128 v[110:113], v221 offset:6144
	s_mul_i32 s7, s3, 0xc000
	v_add_u32_e32 v218, s7, v78
	s_nop 0
	v_readfirstlane_b32 s7, v218
	s_add_u32 m0, s7, 0x0
	s_nop 0
	global_load_lds_dwordx4 v222, s[4:5]
	s_add_u32 m0, s7, 0x2000
	s_nop 0
	global_load_lds_dwordx4 v223, s[4:5]
	s_add_u32 m0, s7, 0x4000
	s_nop 0
	global_load_lds_dwordx4 v224, s[4:5]
	s_add_u32 m0, s7, 0x6000
	s_nop 0
	global_load_lds_dwordx4 v225, s[4:5]
	s_add_u32 m0, s7, 0x8000
	s_nop 0
	global_load_lds_dwordx4 v222, s[42:43]
	s_add_u32 m0, s7, 0xa000
	s_nop 0
	global_load_lds_dwordx4 v223, s[42:43]
	ds_read_b128 v[114:117], v220 offset:1024
	ds_read_b128 v[118:121], v220 offset:3072
	ds_read_b128 v[122:125], v220 offset:5120
	ds_read_b128 v[126:129], v220 offset:7168
	ds_read_b128 v[134:137], v221 offset:1024
	ds_read_b128 v[138:141], v221 offset:3072
	ds_read_b128 v[162:165], v221 offset:5120
	ds_read_b128 v[166:169], v221 offset:7168
	s_waitcnt lgkmcnt(8)
	v_mfma_f32_16x16x32_bf16 v[62:65], v[98:101], v[82:85], v[62:65]
	v_mfma_f32_16x16x32_bf16 v[58:61], v[102:105], v[82:85], v[58:61]
	v_mfma_f32_16x16x32_bf16 v[54:57], v[106:109], v[82:85], v[54:57]
	v_mfma_f32_16x16x32_bf16 v[50:53], v[110:113], v[82:85], v[50:53]
	v_mfma_f32_16x16x32_bf16 v[46:49], v[98:101], v[86:89], v[46:49]
	v_mfma_f32_16x16x32_bf16 v[42:45], v[102:105], v[86:89], v[42:45]
	v_mfma_f32_16x16x32_bf16 v[38:41], v[106:109], v[86:89], v[38:41]
	v_mfma_f32_16x16x32_bf16 v[34:37], v[110:113], v[86:89], v[34:37]
	v_mfma_f32_16x16x32_bf16 v[30:33], v[98:101], v[90:93], v[30:33]
	v_mfma_f32_16x16x32_bf16 v[26:29], v[102:105], v[90:93], v[26:29]
	v_mfma_f32_16x16x32_bf16 v[22:25], v[106:109], v[90:93], v[22:25]
	v_mfma_f32_16x16x32_bf16 v[18:21], v[110:113], v[90:93], v[18:21]
	v_mfma_f32_16x16x32_bf16 v[14:17], v[98:101], v[94:97], v[14:17]
	v_mfma_f32_16x16x32_bf16 v[10:13], v[102:105], v[94:97], v[10:13]
	v_mfma_f32_16x16x32_bf16 v[6:9], v[106:109], v[94:97], v[6:9]
	v_mfma_f32_16x16x32_bf16 v[2:5], v[110:113], v[94:97], v[2:5]
	s_waitcnt lgkmcnt(0)
	s_add_i32 s7, s6, 1
	s_cmp_lg_u32 s6, 2
	s_cselect_b32 s6, s7, 0
	s_add_i32 s7, s3, 1
	s_cmp_lg_u32 s3, 2
	s_cselect_b32 s3, s7, 0
	s_add_u32 s4, s4, 0x800
	s_addc_u32 s5, s5, 0
	s_add_u32 s42, s42, 0x800
	s_addc_u32 s43, s43, 0
	s_sub_u32 s32, s32, 1
.Lgbl_gwin:
	s_waitcnt vmcnt(6)
	s_barrier
	s_mul_i32 s7, s6, 0xc000
	v_add_u32_e32 v220, s7, v80
	v_add_u32_e32 v221, s7, v79
	ds_read_b128 v[82:85], v220 offset:0
	ds_read_b128 v[86:89], v220 offset:2048
	ds_read_b128 v[90:93], v220 offset:4096
	ds_read_b128 v[94:97], v220 offset:6144
	ds_read_b128 v[98:101], v221 offset:0
	ds_read_b128 v[102:105], v221 offset:2048
	ds_read_b128 v[106:109], v221 offset:4096
	ds_read_b128 v[110:113], v221 offset:6144
	s_mul_i32 s7, s3, 0xc000
	v_add_u32_e32 v218, s7, v78
	s_nop 0
	v_readfirstlane_b32 s7, v218
	v_mfma_f32_16x16x32_bf16 v[62:65], v[134:137], v[114:117], v[62:65]
	v_mfma_f32_16x16x32_bf16 v[58:61], v[138:141], v[114:117], v[58:61]
	s_add_u32 m0, s7, 0x0
	s_nop 0
	global_load_lds_dwordx4 v222, s[4:5]
	v_mfma_f32_16x16x32_bf16 v[54:57], v[162:165], v[114:117], v[54:57]
	v_mfma_f32_16x16x32_bf16 v[50:53], v[166:169], v[114:117], v[50:53]
	s_add_u32 m0, s7, 0x2000
	s_nop 0
	global_load_lds_dwordx4 v223, s[4:5]
	v_mfma_f32_16x16x32_bf16 v[46:49], v[134:137], v[118:121], v[46:49]
	v_mfma_f32_16x16x32_bf16 v[42:45], v[138:141], v[118:121], v[42:45]
	s_add_u32 m0, s7, 0x4000
	s_nop 0
	global_load_lds_dwordx4 v224, s[4:5]
	v_mfma_f32_16x16x32_bf16 v[38:41], v[162:165], v[118:121], v[38:41]
	v_mfma_f32_16x16x32_bf16 v[34:37], v[166:169], v[118:121], v[34:37]
	s_add_u32 m0, s7, 0x6000
	s_nop 0
	global_load_lds_dwordx4 v225, s[4:5]
	v_mfma_f32_16x16x32_bf16 v[30:33], v[134:137], v[122:125], v[30:33]
	v_mfma_f32_16x16x32_bf16 v[26:29], v[138:141], v[122:125], v[26:29]
	s_add_u32 m0, s7, 0x8000
	s_nop 0
	global_load_lds_dwordx4 v222, s[42:43]
	v_mfma_f32_16x16x32_bf16 v[22:25], v[162:165], v[122:125], v[22:25]
	v_mfma_f32_16x16x32_bf16 v[18:21], v[166:169], v[122:125], v[18:21]
	s_add_u32 m0, s7, 0xa000
	s_nop 0
	global_load_lds_dwordx4 v223, s[42:43]
	v_mfma_f32_16x16x32_bf16 v[14:17], v[134:137], v[126:129], v[14:17]
	v_mfma_f32_16x16x32_bf16 v[10:13], v[138:141], v[126:129], v[10:13]
	v_mfma_f32_16x16x32_bf16 v[6:9], v[162:165], v[126:129], v[6:9]
	v_mfma_f32_16x16x32_bf16 v[2:5], v[166:169], v[126:129], v[2:5]
	ds_read_b128 v[114:117], v220 offset:1024
	ds_read_b128 v[118:121], v220 offset:3072
	ds_read_b128 v[122:125], v220 offset:5120
	ds_read_b128 v[126:129], v220 offset:7168
	ds_read_b128 v[134:137], v221 offset:1024
	ds_read_b128 v[138:141], v221 offset:3072
	ds_read_b128 v[162:165], v221 offset:5120
	ds_read_b128 v[166:169], v221 offset:7168
	s_waitcnt lgkmcnt(8)
	v_mfma_f32_16x16x32_bf16 v[62:65], v[98:101], v[82:85], v[62:65]
	v_mfma_f32_16x16x32_bf16 v[58:61], v[102:105], v[82:85], v[58:61]
	v_mfma_f32_16x16x32_bf16 v[54:57], v[106:109], v[82:85], v[54:57]
	v_mfma_f32_16x16x32_bf16 v[50:53], v[110:113], v[82:85], v[50:53]
	v_mfma_f32_16x16x32_bf16 v[46:49], v[98:101], v[86:89], v[46:49]
	v_mfma_f32_16x16x32_bf16 v[42:45], v[102:105], v[86:89], v[42:45]
	v_mfma_f32_16x16x32_bf16 v[38:41], v[106:109], v[86:89], v[38:41]
	v_mfma_f32_16x16x32_bf16 v[34:37], v[110:113], v[86:89], v[34:37]
	v_mfma_f32_16x16x32_bf16 v[30:33], v[98:101], v[90:93], v[30:33]
	v_mfma_f32_16x16x32_bf16 v[26:29], v[102:105], v[90:93], v[26:29]
	v_mfma_f32_16x16x32_bf16 v[22:25], v[106:109], v[90:93], v[22:25]
	v_mfma_f32_16x16x32_bf16 v[18:21], v[110:113], v[90:93], v[18:21]
	v_mfma_f32_16x16x32_bf16 v[14:17], v[98:101], v[94:97], v[14:17]
	v_mfma_f32_16x16x32_bf16 v[10:13], v[102:105], v[94:97], v[10:13]
	v_mfma_f32_16x16x32_bf16 v[6:9], v[106:109], v[94:97], v[6:9]
	v_mfma_f32_16x16x32_bf16 v[2:5], v[110:113], v[94:97], v[2:5]
	s_waitcnt lgkmcnt(0)
	s_add_i32 s7, s6, 1
	s_cmp_lg_u32 s6, 2
	s_cselect_b32 s6, s7, 0
	s_add_i32 s7, s3, 1
	s_cmp_lg_u32 s3, 2
	s_cselect_b32 s3, s7, 0
	s_add_u32 s4, s4, 0x800
	s_addc_u32 s5, s5, 0
	s_add_u32 s42, s42, 0x800
	s_addc_u32 s43, s43, 0
	s_sub_u32 s32, s32, 1
	s_cmp_lg_u32 s32, 0
	s_cbranch_scc1 .Lgbl_gwin
	s_waitcnt vmcnt(6)
	s_barrier
	s_mul_i32 s7, s6, 0xc000
	v_add_u32_e32 v220, s7, v80
	v_add_u32_e32 v221, s7, v79
	ds_read_b128 v[82:85], v220 offset:0
	ds_read_b128 v[86:89], v220 offset:2048
	ds_read_b128 v[90:93], v220 offset:4096
	ds_read_b128 v[94:97], v220 offset:6144
	ds_read_b128 v[98:101], v221 offset:0
	ds_read_b128 v[102:105], v221 offset:2048
	ds_read_b128 v[106:109], v221 offset:4096
	ds_read_b128 v[110:113], v221 offset:6144
	v_mfma_f32_16x16x32_bf16 v[62:65], v[134:137], v[114:117], v[62:65]
	v_mfma_f32_16x16x32_bf16 v[58:61], v[138:141], v[114:117], v[58:61]
	v_mfma_f32_16x16x32_bf16 v[54:57], v[162:165], v[114:117], v[54:57]
	v_mfma_f32_16x16x32_bf16 v[50:53], v[166:169], v[114:117], v[50:53]
	v_mfma_f32_16x16x32_bf16 v[46:49], v[134:137], v[118:121], v[46:49]
	v_mfma_f32_16x16x32_bf16 v[42:45], v[138:141], v[118:121], v[42:45]
	v_mfma_f32_16x16x32_bf16 v[38:41], v[162:165], v[118:121], v[38:41]
	v_mfma_f32_16x16x32_bf16 v[34:37], v[166:169], v[118:121], v[34:37]
	v_mfma_f32_16x16x32_bf16 v[30:33], v[134:137], v[122:125], v[30:33]
	v_mfma_f32_16x16x32_bf16 v[26:29], v[138:141], v[122:125], v[26:29]
	v_mfma_f32_16x16x32_bf16 v[22:25], v[162:165], v[122:125], v[22:25]
	v_mfma_f32_16x16x32_bf16 v[18:21], v[166:169], v[122:125], v[18:21]
	v_mfma_f32_16x16x32_bf16 v[14:17], v[134:137], v[126:129], v[14:17]
	v_mfma_f32_16x16x32_bf16 v[10:13], v[138:141], v[126:129], v[10:13]
	v_mfma_f32_16x16x32_bf16 v[6:9], v[162:165], v[126:129], v[6:9]
	v_mfma_f32_16x16x32_bf16 v[2:5], v[166:169], v[126:129], v[2:5]
	ds_read_b128 v[114:117], v220 offset:1024
	ds_read_b128 v[118:121], v220 offset:3072
	ds_read_b128 v[122:125], v220 offset:5120
	ds_read_b128 v[126:129], v220 offset:7168
	ds_read_b128 v[134:137], v221 offset:1024
	ds_read_b128 v[138:141], v221 offset:3072
	ds_read_b128 v[162:165], v221 offset:5120
	ds_read_b128 v[166:169], v221 offset:7168
	s_waitcnt lgkmcnt(8)
	v_mfma_f32_16x16x32_bf16 v[62:65], v[98:101], v[82:85], v[62:65]
	v_mfma_f32_16x16x32_bf16 v[58:61], v[102:105], v[82:85], v[58:61]
	v_mfma_f32_16x16x32_bf16 v[54:57], v[106:109], v[82:85], v[54:57]
	v_mfma_f32_16x16x32_bf16 v[50:53], v[110:113], v[82:85], v[50:53]
	v_mfma_f32_16x16x32_bf16 v[46:49], v[98:101], v[86:89], v[46:49]
	v_mfma_f32_16x16x32_bf16 v[42:45], v[102:105], v[86:89], v[42:45]
	v_mfma_f32_16x16x32_bf16 v[38:41], v[106:109], v[86:89], v[38:41]
	v_mfma_f32_16x16x32_bf16 v[34:37], v[110:113], v[86:89], v[34:37]
	v_mfma_f32_16x16x32_bf16 v[30:33], v[98:101], v[90:93], v[30:33]
	v_mfma_f32_16x16x32_bf16 v[26:29], v[102:105], v[90:93], v[26:29]
	v_mfma_f32_16x16x32_bf16 v[22:25], v[106:109], v[90:93], v[22:25]
	v_mfma_f32_16x16x32_bf16 v[18:21], v[110:113], v[90:93], v[18:21]
	v_mfma_f32_16x16x32_bf16 v[14:17], v[98:101], v[94:97], v[14:17]
	v_mfma_f32_16x16x32_bf16 v[10:13], v[102:105], v[94:97], v[10:13]
	v_mfma_f32_16x16x32_bf16 v[6:9], v[106:109], v[94:97], v[6:9]
	v_mfma_f32_16x16x32_bf16 v[2:5], v[110:113], v[94:97], v[2:5]
	s_waitcnt lgkmcnt(0)
	s_add_i32 s7, s6, 1
	s_cmp_lg_u32 s6, 2
	s_cselect_b32 s6, s7, 0
	s_add_i32 s7, s3, 1
	s_cmp_lg_u32 s3, 2
	s_cselect_b32 s3, s7, 0
	s_waitcnt vmcnt(0)
	s_barrier
	s_mul_i32 s7, s6, 0xc000
	v_add_u32_e32 v220, s7, v80
	v_add_u32_e32 v221, s7, v79
	ds_read_b128 v[82:85], v220 offset:0
	ds_read_b128 v[86:89], v220 offset:2048
	ds_read_b128 v[90:93], v220 offset:4096
	ds_read_b128 v[94:97], v220 offset:6144
	ds_read_b128 v[98:101], v221 offset:0
	ds_read_b128 v[102:105], v221 offset:2048
	ds_read_b128 v[106:109], v221 offset:4096
	ds_read_b128 v[110:113], v221 offset:6144
	v_mfma_f32_16x16x32_bf16 v[62:65], v[134:137], v[114:117], v[62:65]
	v_mfma_f32_16x16x32_bf16 v[58:61], v[138:141], v[114:117], v[58:61]
	v_mfma_f32_16x16x32_bf16 v[54:57], v[162:165], v[114:117], v[54:57]
	v_mfma_f32_16x16x32_bf16 v[50:53], v[166:169], v[114:117], v[50:53]
	v_mfma_f32_16x16x32_bf16 v[46:49], v[134:137], v[118:121], v[46:49]
	v_mfma_f32_16x16x32_bf16 v[42:45], v[138:141], v[118:121], v[42:45]
	v_mfma_f32_16x16x32_bf16 v[38:41], v[162:165], v[118:121], v[38:41]
	v_mfma_f32_16x16x32_bf16 v[34:37], v[166:169], v[118:121], v[34:37]
	v_mfma_f32_16x16x32_bf16 v[30:33], v[134:137], v[122:125], v[30:33]
	v_mfma_f32_16x16x32_bf16 v[26:29], v[138:141], v[122:125], v[26:29]
	v_mfma_f32_16x16x32_bf16 v[22:25], v[162:165], v[122:125], v[22:25]
	v_mfma_f32_16x16x32_bf16 v[18:21], v[166:169], v[122:125], v[18:21]
	v_mfma_f32_16x16x32_bf16 v[14:17], v[134:137], v[126:129], v[14:17]
	v_mfma_f32_16x16x32_bf16 v[10:13], v[138:141], v[126:129], v[10:13]
	v_mfma_f32_16x16x32_bf16 v[6:9], v[162:165], v[126:129], v[6:9]
	v_mfma_f32_16x16x32_bf16 v[2:5], v[166:169], v[126:129], v[2:5]
	ds_read_b128 v[114:117], v220 offset:1024
	ds_read_b128 v[118:121], v220 offset:3072
	ds_read_b128 v[122:125], v220 offset:5120
	ds_read_b128 v[126:129], v220 offset:7168
	ds_read_b128 v[134:137], v221 offset:1024
	ds_read_b128 v[138:141], v221 offset:3072
	ds_read_b128 v[162:165], v221 offset:5120
	ds_read_b128 v[166:169], v221 offset:7168
	s_waitcnt lgkmcnt(8)
	v_mfma_f32_16x16x32_bf16 v[62:65], v[98:101], v[82:85], v[62:65]
	v_mfma_f32_16x16x32_bf16 v[58:61], v[102:105], v[82:85], v[58:61]
	v_mfma_f32_16x16x32_bf16 v[54:57], v[106:109], v[82:85], v[54:57]
	v_mfma_f32_16x16x32_bf16 v[50:53], v[110:113], v[82:85], v[50:53]
	v_mfma_f32_16x16x32_bf16 v[46:49], v[98:101], v[86:89], v[46:49]
	v_mfma_f32_16x16x32_bf16 v[42:45], v[102:105], v[86:89], v[42:45]
	v_mfma_f32_16x16x32_bf16 v[38:41], v[106:109], v[86:89], v[38:41]
	v_mfma_f32_16x16x32_bf16 v[34:37], v[110:113], v[86:89], v[34:37]
	v_mfma_f32_16x16x32_bf16 v[30:33], v[98:101], v[90:93], v[30:33]
	v_mfma_f32_16x16x32_bf16 v[26:29], v[102:105], v[90:93], v[26:29]
	v_mfma_f32_16x16x32_bf16 v[22:25], v[106:109], v[90:93], v[22:25]
	v_mfma_f32_16x16x32_bf16 v[18:21], v[110:113], v[90:93], v[18:21]
	v_mfma_f32_16x16x32_bf16 v[14:17], v[98:101], v[94:97], v[14:17]
	v_mfma_f32_16x16x32_bf16 v[10:13], v[102:105], v[94:97], v[10:13]
	v_mfma_f32_16x16x32_bf16 v[6:9], v[106:109], v[94:97], v[6:9]
	v_mfma_f32_16x16x32_bf16 v[2:5], v[110:113], v[94:97], v[2:5]
	s_waitcnt lgkmcnt(0)
	s_add_i32 s7, s6, 1
	s_cmp_lg_u32 s6, 2
	s_cselect_b32 s6, s7, 0
	s_add_i32 s7, s3, 1
	s_cmp_lg_u32 s3, 2
	s_cselect_b32 s3, s7, 0
	v_mfma_f32_16x16x32_bf16 v[62:65], v[134:137], v[114:117], v[62:65]
	v_mfma_f32_16x16x32_bf16 v[58:61], v[138:141], v[114:117], v[58:61]
	v_mfma_f32_16x16x32_bf16 v[54:57], v[162:165], v[114:117], v[54:57]
	v_mfma_f32_16x16x32_bf16 v[50:53], v[166:169], v[114:117], v[50:53]
	v_mfma_f32_16x16x32_bf16 v[46:49], v[134:137], v[118:121], v[46:49]
	v_mfma_f32_16x16x32_bf16 v[42:45], v[138:141], v[118:121], v[42:45]
	v_mfma_f32_16x16x32_bf16 v[38:41], v[162:165], v[118:121], v[38:41]
	v_mfma_f32_16x16x32_bf16 v[34:37], v[166:169], v[118:121], v[34:37]
	v_mfma_f32_16x16x32_bf16 v[30:33], v[134:137], v[122:125], v[30:33]
	v_mfma_f32_16x16x32_bf16 v[26:29], v[138:141], v[122:125], v[26:29]
	v_mfma_f32_16x16x32_bf16 v[22:25], v[162:165], v[122:125], v[22:25]
	v_mfma_f32_16x16x32_bf16 v[18:21], v[166:169], v[122:125], v[18:21]
	v_mfma_f32_16x16x32_bf16 v[14:17], v[134:137], v[126:129], v[14:17]
	v_mfma_f32_16x16x32_bf16 v[10:13], v[138:141], v[126:129], v[10:13]
	v_mfma_f32_16x16x32_bf16 v[6:9], v[162:165], v[126:129], v[6:9]
	v_mfma_f32_16x16x32_bf16 v[2:5], v[166:169], v[126:129], v[2:5]

.LBB0_337:
	v_mov_b32_e32 v18, v142
	v_mov_b32_e32 v0, v142
	s_lshl_b32 s8, s18, 8
	v_and_b32_e32 v2, 15, v0
	v_lshlrev_b32_e32 v4, 2, v0
	v_and_b32_e32 v3, 48, v0
	v_lshlrev_b32_e32 v2, 6, v2
	v_and_b32_e32 v4, 32, v4
	v_bitop3_b32 v11, v2, v4, v3 bitop3:0x36
	v_lshlrev_b32_e32 v2, 6, v0
	v_and_b32_e32 v2, 0x3c0, v2
	v_bitop3_b32 v14, v2, v4, v3 bitop3:0x36
	v_ashrrev_i32_e32 v2, 31, v0
	v_lshrrev_b32_e32 v2, 26, v2
	v_lshlrev_b32_e32 v12, 4, v0
	v_lshlrev_b32_e32 v5, 7, v0
	v_add_u32_e32 v2, v0, v2
	v_bfe_i32 v0, v0, 27, 1
	v_lshrrev_b32_e32 v0, 22, v0
	v_add_u32_e32 v0, v12, v0
	v_and_b32_e32 v0, 0xfffffc00, v0
	v_sub_u32_e32 v0, v12, v0
	v_ashrrev_i32_e32 v3, 6, v2
	v_lshrrev_b32_e32 v2, 4, v0
	s_and_b32 s0, s16, 0xc0
	v_bitop3_b32 v4, v2, v0, 32 bitop3:0x6c
	v_ashrrev_i32_e32 v0, 31, v0
	s_or_b32 s0, s8, s0
	v_lshrrev_b32_e32 v0, 26, v0
	s_ashr_i32 s1, s0, 31
	v_lshlrev_b32_e32 v2, 3, v3
	v_add_u32_e32 v0, v4, v0
	s_lshl_b32 s2, s19, 7
	s_lshl_b64 s[4:5], s[0:1], 11
	v_and_b32_e32 v2, -16, v2
	v_ashrrev_i32_e32 v0, 6, v0
	s_add_u32 s6, s24, s4
	v_add_u32_e32 v2, v0, v2
	v_mul_i32_i24_e32 v0, 64, v0
	s_addc_u32 s7, s25, s5
	v_mov_b32_e32 v228, s6
	v_mov_b32_e32 v229, s7
	s_ashr_i32 s3, s2, 31
	v_lshlrev_b32_e32 v3, 5, v3
	v_sub_u32_e32 v0, v4, v0
	s_lshl_b64 s[4:5], s[2:3], 11
	v_and_b32_e32 v3, 32, v3
	v_ashrrev_i16_sdwa v0, v146, sext(v0) dst_sel:DWORD dst_unused:UNUSED_PAD src0_sel:DWORD src1_sel:BYTE_0
	s_add_u32 s4, s14, s4
	v_add_u32_sdwa v4, v3, sext(v0) dst_sel:DWORD dst_unused:UNUSED_PAD src0_sel:DWORD src1_sel:WORD_0
	v_ashrrev_i32_e32 v3, 31, v2
	s_addc_u32 s5, s15, s5
	v_mov_b32_e32 v230, s4
	v_mov_b32_e32 v231, s5
	v_and_b32_e32 v13, 0x2000, v5
	v_lshlrev_b64 v[6:7], 11, v[2:3]
	v_ashrrev_i32_e32 v5, 31, v4
	v_lshl_add_u64 v[2:3], s[6:7], 0, v[6:7]
	v_lshlrev_b64 v[4:5], 1, v[4:5]
	v_add_u32_e32 v0, 0, v12
	v_lshl_add_u64 v[6:7], s[4:5], 0, v[6:7]
	v_lshl_add_u64 v[2:3], v[2:3], 0, v[4:5]
	v_lshl_add_u64 v[4:5], v[6:7], 0, v[4:5]
	v_add_u32_e32 v6, 0x8000, v0
	v_add_u32_e32 v15, 0x2000, v12
	v_readfirstlane_b32 s6, v6
	v_ashrrev_i32_e32 v6, 31, v15
	v_lshrrev_b32_e32 v6, 22, v6
	v_add_u32_e32 v6, v15, v6
	v_ashrrev_i32_e32 v7, 10, v6
	v_mul_i32_i24_e32 v6, 0x400, v7
	v_sub_u32_e32 v6, v15, v6
	v_lshrrev_b32_e32 v8, 4, v6
	v_bitop3_b32 v8, v8, v6, 32 bitop3:0x6c
	v_ashrrev_i32_e32 v9, 31, v8
	v_lshrrev_b32_e32 v9, 26, v9
	v_add_u32_e32 v9, v8, v9
	v_lshlrev_b32_e32 v6, 3, v7
	v_ashrrev_i32_e32 v16, 6, v9
	v_and_b32_e32 v9, 0xc0, v9
	v_and_b32_e32 v6, -16, v6
	v_lshlrev_b32_e32 v7, 5, v7
	v_sub_u32_e32 v8, v8, v9
	v_add_u32_e32 v6, v16, v6
	v_and_b32_e32 v7, 32, v7
	v_ashrrev_i16_sdwa v8, v146, sext(v8) dst_sel:DWORD dst_unused:UNUSED_PAD src0_sel:DWORD src1_sel:BYTE_0
	v_add_u32_sdwa v8, v7, sext(v8) dst_sel:DWORD dst_unused:UNUSED_PAD src0_sel:DWORD src1_sel:WORD_0
	v_ashrrev_i32_e32 v7, 31, v6
	v_lshlrev_b64 v[6:7], 11, v[6:7]
	v_readfirstlane_b32 s1, v0
	v_lshl_add_u64 v[6:7], s[4:5], 0, v[6:7]
	v_ashrrev_i32_e32 v9, 31, v8
	s_mov_b32 m0, s1
	v_lshl_add_u64 v[6:7], v[8:9], 1, v[6:7]
	v_add_u32_e32 v8, 0xa000, v0
	v_and_b32_e32 v234, 63, v142
	v_lshlrev_b32_e32 v232, 4, v234
	v_lshrrev_b32_e32 v235, 5, v234
	v_lshlrev_b32_e32 v235, 5, v235
	v_xor_b32_e32 v232, v232, v235
	v_lshrrev_b32_e32 v234, 6, v142
	v_and_b32_e32 v235, 1, v234
	v_lshl_add_u32 v232, v235, 10, v232
	v_lshrrev_b32_e32 v234, 1, v234
	v_lshl_add_u32 v232, v234, 15, v232
	v_mov_b32_e32 v233, 0
	v_lshl_add_u64 v[2:3], v[232:233], 0, v[228:229]
	v_lshl_add_u64 v[4:5], v[232:233], 0, v[230:231]
	v_add_u32_e32 v232, 0x20000, v232
	v_lshl_add_u64 v[6:7], v[232:233], 0, v[230:231]
	s_mov_b64 s[38:39], 0x800
	s_waitcnt vmcnt(0) lgkmcnt(0)
	s_barrier
	global_load_lds_dwordx4 v[2:3], off
	s_mov_b32 m0, s6
	v_readfirstlane_b32 s4, v8
	v_add_u32_e32 v0, 0xc000, v0
	global_load_lds_dwordx4 v[4:5], off
	s_mov_b32 m0, s4
	v_readfirstlane_b32 s7, v0
	v_add_u32_e32 v0, s54, v12
	global_load_lds_dwordx4 v[6:7], off
	v_lshl_add_u64 v[8:9], v[2:3], 0, s[38:39]
	s_mov_b32 m0, s7
	v_readfirstlane_b32 s5, v0
	v_add_u32_e32 v0, s54, v15
	global_load_lds_dwordx4 v[8:9], off
	v_lshl_add_u64 v[8:9], v[4:5], 0, s[38:39]
	s_mov_b32 m0, s5
	v_readfirstlane_b32 s9, v0
	global_load_lds_dwordx4 v[8:9], off
	v_lshl_add_u64 v[8:9], v[6:7], 0, s[38:39]
	s_mov_b32 m0, s9
	v_and_b32_e32 v10, 0xfffff800, v12
	global_load_lds_dwordx4 v[8:9], off
	s_waitcnt vmcnt(3)
	s_add_i32 s10, 0, 0x8000
	v_bfe_u32 v40, v18, 6, 1
	v_add3_u32 v9, v10, 0, v11
	v_add3_u32 v8, v13, s10, v14
	s_barrier
	s_add_i32 s10, 0, 0x18000
	v_add_u32_e32 v0, s10, v12
	s_mov_b32 s20, s89
	s_mov_b64 s[38:39], 0x1000
	v_readfirstlane_b32 s11, v0
	v_add_u32_e32 v0, s20, v12
	v_lshl_add_u64 v[10:11], v[2:3], 0, s[38:39]
	s_mov_b32 m0, s11
	v_readfirstlane_b32 s10, v0
	global_load_lds_dwordx4 v[10:11], off
	v_lshl_add_u64 v[10:11], v[4:5], 0, s[38:39]
	s_mov_b32 m0, s10
	v_add_u32_e32 v0, s20, v15
	global_load_lds_dwordx4 v[10:11], off
	v_lshl_add_u64 v[10:11], v[6:7], 0, s[38:39]
	v_readfirstlane_b32 s38, v0
	s_mov_b32 m0, s38
	s_nop 0
	global_load_lds_dwordx4 v[10:11], off
	ds_read_b128 v[10:13], v9 offset:0
	ds_read_b128 v[14:17], v8 offset:0
	ds_read_b128 v[20:23], v8 offset:2048
	ds_read_b128 v[24:27], v8 offset:4096
	ds_read_b128 v[28:31], v8 offset:6144
	ds_read_b128 v[32:35], v9 offset:1024
	ds_read_b128 v[36:39], v8 offset:1024
	ds_read_b128 v[42:45], v8 offset:3072
	ds_read_b128 v[46:49], v8 offset:5120
	ds_read_b128 v[50:53], v8 offset:7168
	s_waitcnt lgkmcnt(5)
	s_nop 0
	v_mfma_f32_16x16x32_bf16 v[14:17], v[14:17], v[10:13], 0
	v_mfma_f32_16x16x32_bf16 v[20:23], v[20:23], v[10:13], 0
	v_mfma_f32_16x16x32_bf16 v[24:27], v[24:27], v[10:13], 0
	v_mfma_f32_16x16x32_bf16 v[10:13], v[28:31], v[10:13], 0
	s_waitcnt lgkmcnt(0)
	v_mfma_f32_16x16x32_bf16 v[14:17], v[36:39], v[32:35], v[14:17]
	v_mfma_f32_16x16x32_bf16 v[20:23], v[42:45], v[32:35], v[20:23]
	v_mfma_f32_16x16x32_bf16 v[24:27], v[46:49], v[32:35], v[24:27]
	v_mfma_f32_16x16x32_bf16 v[28:31], v[50:53], v[32:35], v[10:13]
	s_waitcnt vmcnt(3)
	s_barrier
	s_mov_b64 s[40:41], 0x1800
	s_mov_b32 m0, s1
	s_nop 0
	v_lshl_add_u64 v[10:11], v[2:3], 0, s[40:41]
	global_load_lds_dwordx4 v[10:11], off
	v_lshl_add_u64 v[10:11], v[4:5], 0, s[40:41]
	s_mov_b32 m0, s6
	v_add_u32_e32 v0, 0xc000, v8
	global_load_lds_dwordx4 v[10:11], off
	v_lshl_add_u64 v[10:11], v[6:7], 0, s[40:41]
	s_mov_b32 m0, s4
	s_nop 0
	global_load_lds_dwordx4 v[10:11], off
	v_add_u32_e32 v10, 0xc000, v9
	ds_read_b128 v[32:35], v10 offset:0
	ds_read_b128 v[36:39], v0 offset:0
	ds_read_b128 v[42:45], v0 offset:2048
	ds_read_b128 v[46:49], v0 offset:4096
	ds_read_b128 v[50:53], v0 offset:6144
	ds_read_b128 v[54:57], v10 offset:1024
	ds_read_b128 v[58:61], v0 offset:1024
	ds_read_b128 v[62:65], v0 offset:3072
	ds_read_b128 v[66:69], v0 offset:5120
	ds_read_b128 v[70:73], v0 offset:7168
	s_waitcnt lgkmcnt(5)
	s_nop 0
	v_mfma_f32_16x16x32_bf16 v[12:15], v[36:39], v[32:35], v[14:17]
	v_mfma_f32_16x16x32_bf16 v[20:23], v[42:45], v[32:35], v[20:23]
	v_mfma_f32_16x16x32_bf16 v[24:27], v[46:49], v[32:35], v[24:27]
	v_mfma_f32_16x16x32_bf16 v[28:31], v[50:53], v[32:35], v[28:31]
	s_waitcnt lgkmcnt(0)
	v_mfma_f32_16x16x32_bf16 v[14:17], v[58:61], v[54:57], v[12:15]
	v_mfma_f32_16x16x32_bf16 v[20:23], v[62:65], v[54:57], v[20:23]
	v_mfma_f32_16x16x32_bf16 v[24:27], v[66:69], v[54:57], v[24:27]
	v_mfma_f32_16x16x32_bf16 v[28:31], v[70:73], v[54:57], v[28:31]
	s_waitcnt vmcnt(3)
	s_barrier
	s_mov_b64 s[40:41], 0x2000
	s_mov_b32 m0, s7
	v_lshl_add_u64 v[12:13], v[2:3], 0, s[40:41]
	global_load_lds_dwordx4 v[12:13], off
	v_lshl_add_u64 v[12:13], v[4:5], 0, s[40:41]
	s_mov_b32 m0, s5
	v_add_u32_e32 v11, 0x18000, v8
	global_load_lds_dwordx4 v[12:13], off
	v_lshl_add_u64 v[12:13], v[6:7], 0, s[40:41]
	s_mov_b32 m0, s9
	s_nop 0
	global_load_lds_dwordx4 v[12:13], off
	v_add_u32_e32 v12, 0x18000, v9
	ds_read_b128 v[32:35], v12 offset:0
	ds_read_b128 v[36:39], v11 offset:0
	ds_read_b128 v[42:45], v11 offset:2048
	ds_read_b128 v[46:49], v11 offset:4096
	ds_read_b128 v[50:53], v11 offset:6144
	ds_read_b128 v[54:57], v12 offset:1024
	ds_read_b128 v[58:61], v11 offset:1024
	ds_read_b128 v[62:65], v11 offset:3072
	ds_read_b128 v[66:69], v11 offset:5120
	ds_read_b128 v[70:73], v11 offset:7168
	s_waitcnt lgkmcnt(5)
	s_nop 0
	v_mfma_f32_16x16x32_bf16 v[14:17], v[36:39], v[32:35], v[14:17]
	v_mfma_f32_16x16x32_bf16 v[20:23], v[42:45], v[32:35], v[20:23]
	v_mfma_f32_16x16x32_bf16 v[24:27], v[46:49], v[32:35], v[24:27]
	v_mfma_f32_16x16x32_bf16 v[28:31], v[50:53], v[32:35], v[28:31]
	s_waitcnt lgkmcnt(0)
	v_mfma_f32_16x16x32_bf16 v[14:17], v[58:61], v[54:57], v[14:17]
	v_mfma_f32_16x16x32_bf16 v[20:23], v[62:65], v[54:57], v[20:23]
	v_mfma_f32_16x16x32_bf16 v[24:27], v[66:69], v[54:57], v[24:27]
	v_mfma_f32_16x16x32_bf16 v[28:31], v[70:73], v[54:57], v[28:31]
	s_waitcnt vmcnt(3)
	s_barrier
	s_mov_b64 s[40:41], 0x2800
	s_mov_b32 m0, s11
	v_lshl_add_u64 v[32:33], v[2:3], 0, s[40:41]
	global_load_lds_dwordx4 v[32:33], off
	v_lshl_add_u64 v[32:33], v[4:5], 0, s[40:41]
	s_mov_b32 m0, s10
	s_nop 0
	global_load_lds_dwordx4 v[32:33], off
	v_lshl_add_u64 v[32:33], v[6:7], 0, s[40:41]
	s_mov_b32 m0, s38
	s_nop 0
	global_load_lds_dwordx4 v[32:33], off
	ds_read_b128 v[32:35], v9 offset:0
	ds_read_b128 v[36:39], v8 offset:0
	ds_read_b128 v[42:45], v8 offset:2048
	ds_read_b128 v[46:49], v8 offset:4096
	ds_read_b128 v[50:53], v8 offset:6144
	ds_read_b128 v[54:57], v9 offset:1024
	ds_read_b128 v[58:61], v8 offset:1024
	ds_read_b128 v[62:65], v8 offset:3072
	ds_read_b128 v[66:69], v8 offset:5120
	ds_read_b128 v[70:73], v8 offset:7168
	s_waitcnt lgkmcnt(5)
	s_nop 0
	v_mfma_f32_16x16x32_bf16 v[14:17], v[36:39], v[32:35], v[14:17]
	v_mfma_f32_16x16x32_bf16 v[20:23], v[42:45], v[32:35], v[20:23]
	v_mfma_f32_16x16x32_bf16 v[24:27], v[46:49], v[32:35], v[24:27]
	v_mfma_f32_16x16x32_bf16 v[28:31], v[50:53], v[32:35], v[28:31]
	s_waitcnt lgkmcnt(0)
	v_mfma_f32_16x16x32_bf16 v[14:17], v[58:61], v[54:57], v[14:17]
	v_mfma_f32_16x16x32_bf16 v[20:23], v[62:65], v[54:57], v[20:23]
	v_mfma_f32_16x16x32_bf16 v[24:27], v[66:69], v[54:57], v[24:27]
	v_mfma_f32_16x16x32_bf16 v[28:31], v[70:73], v[54:57], v[28:31]
	s_waitcnt vmcnt(3)
	s_barrier
	s_mov_b64 s[40:41], 0x3000
	s_mov_b32 m0, s1
	v_lshl_add_u64 v[32:33], v[2:3], 0, s[40:41]
	global_load_lds_dwordx4 v[32:33], off
	v_lshl_add_u64 v[32:33], v[4:5], 0, s[40:41]
	s_mov_b32 m0, s6
	s_nop 0
	global_load_lds_dwordx4 v[32:33], off
	v_lshl_add_u64 v[32:33], v[6:7], 0, s[40:41]
	s_mov_b32 m0, s4
	s_nop 0
	global_load_lds_dwordx4 v[32:33], off
	ds_read_b128 v[32:35], v10 offset:0
	ds_read_b128 v[36:39], v0 offset:0
	ds_read_b128 v[42:45], v0 offset:2048
	ds_read_b128 v[46:49], v0 offset:4096
	ds_read_b128 v[50:53], v0 offset:6144
	ds_read_b128 v[54:57], v10 offset:1024
	ds_read_b128 v[58:61], v0 offset:1024
	ds_read_b128 v[62:65], v0 offset:3072
	ds_read_b128 v[66:69], v0 offset:5120
	ds_read_b128 v[70:73], v0 offset:7168
	s_waitcnt lgkmcnt(5)
	s_nop 0
	v_mfma_f32_16x16x32_bf16 v[14:17], v[36:39], v[32:35], v[14:17]
	v_mfma_f32_16x16x32_bf16 v[20:23], v[42:45], v[32:35], v[20:23]
	v_mfma_f32_16x16x32_bf16 v[24:27], v[46:49], v[32:35], v[24:27]
	v_mfma_f32_16x16x32_bf16 v[28:31], v[50:53], v[32:35], v[28:31]
	s_waitcnt lgkmcnt(0)
	v_mfma_f32_16x16x32_bf16 v[14:17], v[58:61], v[54:57], v[14:17]
	v_mfma_f32_16x16x32_bf16 v[20:23], v[62:65], v[54:57], v[20:23]
	v_mfma_f32_16x16x32_bf16 v[24:27], v[66:69], v[54:57], v[24:27]
	v_mfma_f32_16x16x32_bf16 v[28:31], v[70:73], v[54:57], v[28:31]
	s_waitcnt vmcnt(3)
	s_barrier
	s_mov_b64 s[40:41], 0x3800
	s_mov_b32 m0, s7
	v_lshl_add_u64 v[32:33], v[2:3], 0, s[40:41]
	global_load_lds_dwordx4 v[32:33], off
	v_lshl_add_u64 v[32:33], v[4:5], 0, s[40:41]
	s_mov_b32 m0, s5
	s_nop 0
	global_load_lds_dwordx4 v[32:33], off
	v_lshl_add_u64 v[32:33], v[6:7], 0, s[40:41]
	s_mov_b32 m0, s9
	s_nop 0
	global_load_lds_dwordx4 v[32:33], off
	ds_read_b128 v[32:35], v12 offset:0
	ds_read_b128 v[36:39], v11 offset:0
	ds_read_b128 v[42:45], v11 offset:2048
	ds_read_b128 v[46:49], v11 offset:4096
	ds_read_b128 v[50:53], v11 offset:6144
	ds_read_b128 v[54:57], v12 offset:1024
	ds_read_b128 v[58:61], v11 offset:1024
	ds_read_b128 v[62:65], v11 offset:3072
	ds_read_b128 v[66:69], v11 offset:5120
	ds_read_b128 v[70:73], v11 offset:7168
	s_waitcnt lgkmcnt(5)
	s_nop 0
	v_mfma_f32_16x16x32_bf16 v[14:17], v[36:39], v[32:35], v[14:17]
	v_mfma_f32_16x16x32_bf16 v[20:23], v[42:45], v[32:35], v[20:23]
	v_mfma_f32_16x16x32_bf16 v[24:27], v[46:49], v[32:35], v[24:27]
	v_mfma_f32_16x16x32_bf16 v[28:31], v[50:53], v[32:35], v[28:31]
	s_waitcnt lgkmcnt(0)
	v_mfma_f32_16x16x32_bf16 v[14:17], v[58:61], v[54:57], v[14:17]
	v_mfma_f32_16x16x32_bf16 v[20:23], v[62:65], v[54:57], v[20:23]
	v_mfma_f32_16x16x32_bf16 v[24:27], v[66:69], v[54:57], v[24:27]
	v_mfma_f32_16x16x32_bf16 v[28:31], v[70:73], v[54:57], v[28:31]
	s_waitcnt vmcnt(3)
	s_barrier
	s_mov_b64 s[40:41], 0x4000
	s_mov_b32 m0, s11
	v_lshl_add_u64 v[32:33], v[2:3], 0, s[40:41]
	global_load_lds_dwordx4 v[32:33], off
	v_lshl_add_u64 v[32:33], v[4:5], 0, s[40:41]
	s_mov_b32 m0, s10
	s_nop 0
	global_load_lds_dwordx4 v[32:33], off
	v_lshl_add_u64 v[32:33], v[6:7], 0, s[40:41]
	s_mov_b32 m0, s38
	s_nop 0
	global_load_lds_dwordx4 v[32:33], off
	ds_read_b128 v[32:35], v9 offset:0
	ds_read_b128 v[36:39], v8 offset:0
	ds_read_b128 v[42:45], v8 offset:2048
	ds_read_b128 v[46:49], v8 offset:4096
	ds_read_b128 v[50:53], v8 offset:6144
	ds_read_b128 v[54:57], v9 offset:1024
	ds_read_b128 v[58:61], v8 offset:1024
	ds_read_b128 v[62:65], v8 offset:3072
	ds_read_b128 v[66:69], v8 offset:5120
	ds_read_b128 v[70:73], v8 offset:7168
	s_waitcnt lgkmcnt(5)
	s_nop 0
	v_mfma_f32_16x16x32_bf16 v[14:17], v[36:39], v[32:35], v[14:17]
	v_mfma_f32_16x16x32_bf16 v[20:23], v[42:45], v[32:35], v[20:23]
	v_mfma_f32_16x16x32_bf16 v[24:27], v[46:49], v[32:35], v[24:27]
	v_mfma_f32_16x16x32_bf16 v[28:31], v[50:53], v[32:35], v[28:31]
	s_waitcnt lgkmcnt(0)
	v_mfma_f32_16x16x32_bf16 v[14:17], v[58:61], v[54:57], v[14:17]
	v_mfma_f32_16x16x32_bf16 v[20:23], v[62:65], v[54:57], v[20:23]
	v_mfma_f32_16x16x32_bf16 v[24:27], v[66:69], v[54:57], v[24:27]
	v_mfma_f32_16x16x32_bf16 v[28:31], v[70:73], v[54:57], v[28:31]
	s_waitcnt vmcnt(3)
	s_barrier
	s_mov_b64 s[40:41], 0x4800
	s_mov_b32 m0, s1
	v_lshl_add_u64 v[32:33], v[2:3], 0, s[40:41]
	global_load_lds_dwordx4 v[32:33], off
	v_lshl_add_u64 v[32:33], v[4:5], 0, s[40:41]
	s_mov_b32 m0, s6
	s_nop 0
	global_load_lds_dwordx4 v[32:33], off
	v_lshl_add_u64 v[32:33], v[6:7], 0, s[40:41]
	s_mov_b32 m0, s4
	s_nop 0
	global_load_lds_dwordx4 v[32:33], off
	ds_read_b128 v[32:35], v10 offset:0
	ds_read_b128 v[36:39], v0 offset:0
	ds_read_b128 v[42:45], v0 offset:2048
	ds_read_b128 v[46:49], v0 offset:4096
	ds_read_b128 v[50:53], v0 offset:6144
	ds_read_b128 v[54:57], v10 offset:1024
	ds_read_b128 v[58:61], v0 offset:1024
	ds_read_b128 v[62:65], v0 offset:3072
	ds_read_b128 v[66:69], v0 offset:5120
	ds_read_b128 v[70:73], v0 offset:7168
	s_waitcnt lgkmcnt(5)
	s_nop 0
	v_mfma_f32_16x16x32_bf16 v[14:17], v[36:39], v[32:35], v[14:17]
	v_mfma_f32_16x16x32_bf16 v[20:23], v[42:45], v[32:35], v[20:23]
	v_mfma_f32_16x16x32_bf16 v[24:27], v[46:49], v[32:35], v[24:27]
	v_mfma_f32_16x16x32_bf16 v[28:31], v[50:53], v[32:35], v[28:31]
	s_waitcnt lgkmcnt(0)
	v_mfma_f32_16x16x32_bf16 v[14:17], v[58:61], v[54:57], v[14:17]
	v_mfma_f32_16x16x32_bf16 v[20:23], v[62:65], v[54:57], v[20:23]
	v_mfma_f32_16x16x32_bf16 v[24:27], v[66:69], v[54:57], v[24:27]
	v_mfma_f32_16x16x32_bf16 v[28:31], v[70:73], v[54:57], v[28:31]
	s_waitcnt vmcnt(3)
	s_barrier
	s_mov_b64 s[40:41], 0x5000
	s_mov_b32 m0, s7
	v_lshl_add_u64 v[32:33], v[2:3], 0, s[40:41]
	global_load_lds_dwordx4 v[32:33], off
	v_lshl_add_u64 v[32:33], v[4:5], 0, s[40:41]
	s_mov_b32 m0, s5
	s_nop 0
	global_load_lds_dwordx4 v[32:33], off
	v_lshl_add_u64 v[32:33], v[6:7], 0, s[40:41]
	s_mov_b32 m0, s9
	s_nop 0
	global_load_lds_dwordx4 v[32:33], off
	ds_read_b128 v[32:35], v12 offset:0
	ds_read_b128 v[36:39], v11 offset:0
	ds_read_b128 v[42:45], v11 offset:2048
	ds_read_b128 v[46:49], v11 offset:4096
	ds_read_b128 v[50:53], v11 offset:6144
	ds_read_b128 v[54:57], v12 offset:1024
	ds_read_b128 v[58:61], v11 offset:1024
	ds_read_b128 v[62:65], v11 offset:3072
	ds_read_b128 v[66:69], v11 offset:5120
	ds_read_b128 v[70:73], v11 offset:7168
	s_waitcnt lgkmcnt(5)
	s_nop 0
	v_mfma_f32_16x16x32_bf16 v[14:17], v[36:39], v[32:35], v[14:17]
	v_mfma_f32_16x16x32_bf16 v[20:23], v[42:45], v[32:35], v[20:23]
	v_mfma_f32_16x16x32_bf16 v[24:27], v[46:49], v[32:35], v[24:27]
	v_mfma_f32_16x16x32_bf16 v[28:31], v[50:53], v[32:35], v[28:31]
	s_waitcnt lgkmcnt(0)
	v_mfma_f32_16x16x32_bf16 v[14:17], v[58:61], v[54:57], v[14:17]
	v_mfma_f32_16x16x32_bf16 v[20:23], v[62:65], v[54:57], v[20:23]
	v_mfma_f32_16x16x32_bf16 v[24:27], v[66:69], v[54:57], v[24:27]
	v_mfma_f32_16x16x32_bf16 v[28:31], v[70:73], v[54:57], v[28:31]
	s_waitcnt vmcnt(3)
	s_barrier
	s_mov_b64 s[40:41], 0x5800
	s_mov_b32 m0, s11
	v_lshl_add_u64 v[32:33], v[2:3], 0, s[40:41]
	global_load_lds_dwordx4 v[32:33], off
	v_lshl_add_u64 v[32:33], v[4:5], 0, s[40:41]
	s_mov_b32 m0, s10
	s_nop 0
	global_load_lds_dwordx4 v[32:33], off
	v_lshl_add_u64 v[32:33], v[6:7], 0, s[40:41]
	s_mov_b32 m0, s38
	s_nop 0
	global_load_lds_dwordx4 v[32:33], off
	ds_read_b128 v[32:35], v9 offset:0
	ds_read_b128 v[36:39], v8 offset:0
	ds_read_b128 v[42:45], v8 offset:2048
	ds_read_b128 v[46:49], v8 offset:4096
	ds_read_b128 v[50:53], v8 offset:6144
	ds_read_b128 v[54:57], v9 offset:1024
	ds_read_b128 v[58:61], v8 offset:1024
	ds_read_b128 v[62:65], v8 offset:3072
	ds_read_b128 v[66:69], v8 offset:5120
	ds_read_b128 v[70:73], v8 offset:7168
	s_waitcnt lgkmcnt(5)
	s_nop 0
	v_mfma_f32_16x16x32_bf16 v[14:17], v[36:39], v[32:35], v[14:17]
	v_mfma_f32_16x16x32_bf16 v[20:23], v[42:45], v[32:35], v[20:23]
	v_mfma_f32_16x16x32_bf16 v[24:27], v[46:49], v[32:35], v[24:27]
	v_mfma_f32_16x16x32_bf16 v[28:31], v[50:53], v[32:35], v[28:31]
	s_waitcnt lgkmcnt(0)
	v_mfma_f32_16x16x32_bf16 v[14:17], v[58:61], v[54:57], v[14:17]
	v_mfma_f32_16x16x32_bf16 v[20:23], v[62:65], v[54:57], v[20:23]
	v_mfma_f32_16x16x32_bf16 v[24:27], v[66:69], v[54:57], v[24:27]
	v_mfma_f32_16x16x32_bf16 v[28:31], v[70:73], v[54:57], v[28:31]
	s_waitcnt vmcnt(3)
	s_barrier
	s_mov_b64 s[40:41], 0x6000
	s_mov_b32 m0, s1
	v_lshl_add_u64 v[32:33], v[2:3], 0, s[40:41]
	global_load_lds_dwordx4 v[32:33], off
	v_lshl_add_u64 v[32:33], v[4:5], 0, s[40:41]
	s_mov_b32 m0, s6
	s_nop 0
	global_load_lds_dwordx4 v[32:33], off
	v_lshl_add_u64 v[32:33], v[6:7], 0, s[40:41]
	s_mov_b32 m0, s4
	s_nop 0
	global_load_lds_dwordx4 v[32:33], off
	ds_read_b128 v[32:35], v10 offset:0
	ds_read_b128 v[36:39], v0 offset:0
	ds_read_b128 v[42:45], v0 offset:2048
	ds_read_b128 v[46:49], v0 offset:4096
	ds_read_b128 v[50:53], v0 offset:6144
	ds_read_b128 v[54:57], v10 offset:1024
	ds_read_b128 v[58:61], v0 offset:1024
	ds_read_b128 v[62:65], v0 offset:3072
	ds_read_b128 v[66:69], v0 offset:5120
	ds_read_b128 v[70:73], v0 offset:7168
	s_waitcnt lgkmcnt(5)
	s_nop 0
	v_mfma_f32_16x16x32_bf16 v[14:17], v[36:39], v[32:35], v[14:17]
	v_mfma_f32_16x16x32_bf16 v[20:23], v[42:45], v[32:35], v[20:23]
	v_mfma_f32_16x16x32_bf16 v[24:27], v[46:49], v[32:35], v[24:27]
	v_mfma_f32_16x16x32_bf16 v[28:31], v[50:53], v[32:35], v[28:31]
	s_waitcnt lgkmcnt(0)
	v_mfma_f32_16x16x32_bf16 v[14:17], v[58:61], v[54:57], v[14:17]
	v_mfma_f32_16x16x32_bf16 v[20:23], v[62:65], v[54:57], v[20:23]
	v_mfma_f32_16x16x32_bf16 v[24:27], v[66:69], v[54:57], v[24:27]
	v_mfma_f32_16x16x32_bf16 v[28:31], v[70:73], v[54:57], v[28:31]
	s_waitcnt vmcnt(3)
	s_barrier
	s_mov_b64 s[40:41], 0x6800
	s_mov_b32 m0, s7
	v_lshl_add_u64 v[32:33], v[2:3], 0, s[40:41]
	global_load_lds_dwordx4 v[32:33], off
	v_lshl_add_u64 v[32:33], v[4:5], 0, s[40:41]
	s_mov_b32 m0, s5
	s_nop 0
	global_load_lds_dwordx4 v[32:33], off
	v_lshl_add_u64 v[32:33], v[6:7], 0, s[40:41]
	s_mov_b32 m0, s9
	s_nop 0
	global_load_lds_dwordx4 v[32:33], off
	ds_read_b128 v[32:35], v12 offset:0
	ds_read_b128 v[36:39], v11 offset:0
	ds_read_b128 v[42:45], v11 offset:2048
	ds_read_b128 v[46:49], v11 offset:4096
	ds_read_b128 v[50:53], v11 offset:6144
	ds_read_b128 v[54:57], v12 offset:1024
	ds_read_b128 v[58:61], v11 offset:1024
	ds_read_b128 v[62:65], v11 offset:3072
	ds_read_b128 v[66:69], v11 offset:5120
	ds_read_b128 v[70:73], v11 offset:7168
	s_waitcnt lgkmcnt(5)
	s_nop 0
	v_mfma_f32_16x16x32_bf16 v[14:17], v[36:39], v[32:35], v[14:17]
	v_mfma_f32_16x16x32_bf16 v[20:23], v[42:45], v[32:35], v[20:23]
	v_mfma_f32_16x16x32_bf16 v[24:27], v[46:49], v[32:35], v[24:27]
	v_mfma_f32_16x16x32_bf16 v[28:31], v[50:53], v[32:35], v[28:31]
	s_waitcnt lgkmcnt(0)
	v_mfma_f32_16x16x32_bf16 v[14:17], v[58:61], v[54:57], v[14:17]
	v_mfma_f32_16x16x32_bf16 v[20:23], v[62:65], v[54:57], v[20:23]
	v_mfma_f32_16x16x32_bf16 v[24:27], v[66:69], v[54:57], v[24:27]
	v_mfma_f32_16x16x32_bf16 v[28:31], v[70:73], v[54:57], v[28:31]
	s_waitcnt vmcnt(3)
	s_barrier
	s_mov_b64 s[40:41], 0x7000
	s_mov_b32 m0, s11
	v_lshl_add_u64 v[32:33], v[2:3], 0, s[40:41]
	global_load_lds_dwordx4 v[32:33], off
	v_lshl_add_u64 v[32:33], v[4:5], 0, s[40:41]
	s_mov_b32 m0, s10
	s_nop 0
	global_load_lds_dwordx4 v[32:33], off
	v_lshl_add_u64 v[32:33], v[6:7], 0, s[40:41]
	s_mov_b32 m0, s38
	s_nop 0
	global_load_lds_dwordx4 v[32:33], off
	ds_read_b128 v[32:35], v9 offset:0
	ds_read_b128 v[36:39], v8 offset:0
	ds_read_b128 v[42:45], v8 offset:2048
	ds_read_b128 v[46:49], v8 offset:4096
	ds_read_b128 v[50:53], v8 offset:6144
	ds_read_b128 v[54:57], v9 offset:1024
	ds_read_b128 v[58:61], v8 offset:1024
	ds_read_b128 v[62:65], v8 offset:3072
	ds_read_b128 v[66:69], v8 offset:5120
	ds_read_b128 v[70:73], v8 offset:7168
	s_waitcnt lgkmcnt(5)
	s_nop 0
	v_mfma_f32_16x16x32_bf16 v[14:17], v[36:39], v[32:35], v[14:17]
	v_mfma_f32_16x16x32_bf16 v[20:23], v[42:45], v[32:35], v[20:23]
	v_mfma_f32_16x16x32_bf16 v[24:27], v[46:49], v[32:35], v[24:27]
	v_mfma_f32_16x16x32_bf16 v[28:31], v[50:53], v[32:35], v[28:31]
	s_waitcnt lgkmcnt(0)
	v_mfma_f32_16x16x32_bf16 v[14:17], v[58:61], v[54:57], v[14:17]
	v_mfma_f32_16x16x32_bf16 v[20:23], v[62:65], v[54:57], v[20:23]
	v_mfma_f32_16x16x32_bf16 v[24:27], v[66:69], v[54:57], v[24:27]
	v_mfma_f32_16x16x32_bf16 v[28:31], v[70:73], v[54:57], v[28:31]
	s_waitcnt vmcnt(3)
	s_barrier
	s_mov_b64 s[10:11], 0x7800
	s_mov_b32 m0, s1
	v_lshl_add_u64 v[2:3], v[2:3], 0, s[10:11]
	global_load_lds_dwordx4 v[2:3], off
	v_lshl_add_u64 v[2:3], v[4:5], 0, s[10:11]
	s_mov_b32 m0, s6
	s_nop 0
	global_load_lds_dwordx4 v[2:3], off
	v_lshl_add_u64 v[2:3], v[6:7], 0, s[10:11]
	s_mov_b32 m0, s4
	s_nop 0
	global_load_lds_dwordx4 v[2:3], off
	ds_read_b128 v[2:5], v10 offset:0
	ds_read_b128 v[32:35], v0 offset:0
	ds_read_b128 v[36:39], v0 offset:2048
	ds_read_b128 v[42:45], v0 offset:4096
	ds_read_b128 v[46:49], v0 offset:6144
	ds_read_b128 v[50:53], v10 offset:1024
	ds_read_b128 v[54:57], v0 offset:1024
	ds_read_b128 v[58:61], v0 offset:3072
	ds_read_b128 v[62:65], v0 offset:5120
	ds_read_b128 v[66:69], v0 offset:7168
	s_waitcnt lgkmcnt(5)
	s_nop 0
	v_mfma_f32_16x16x32_bf16 v[14:17], v[32:35], v[2:5], v[14:17]
	v_mfma_f32_16x16x32_bf16 v[20:23], v[36:39], v[2:5], v[20:23]
	v_mfma_f32_16x16x32_bf16 v[24:27], v[42:45], v[2:5], v[24:27]
	v_mfma_f32_16x16x32_bf16 v[2:5], v[46:49], v[2:5], v[28:31]
	s_waitcnt lgkmcnt(0)
	v_mfma_f32_16x16x32_bf16 v[14:17], v[54:57], v[50:53], v[14:17]
	v_mfma_f32_16x16x32_bf16 v[2:5], v[66:69], v[50:53], v[2:5]
	v_mfma_f32_16x16x32_bf16 v[20:23], v[58:61], v[50:53], v[20:23]
	v_mfma_f32_16x16x32_bf16 v[24:27], v[62:65], v[50:53], v[24:27]
	s_waitcnt vmcnt(3)
	s_barrier
	ds_read_b128 v[28:31], v12 offset:0
	ds_read_b128 v[32:35], v11 offset:0
	ds_read_b128 v[36:39], v11 offset:2048
	ds_read_b128 v[42:45], v11 offset:4096
	ds_read_b128 v[46:49], v11 offset:6144
	ds_read_b128 v[50:53], v12 offset:1024
	ds_read_b128 v[54:57], v11 offset:1024
	ds_read_b128 v[58:61], v11 offset:3072
	ds_read_b128 v[62:65], v11 offset:5120
	ds_read_b128 v[10:13], v11 offset:7168
	s_waitcnt lgkmcnt(5)
	s_nop 0
	v_mfma_f32_16x16x32_bf16 v[14:17], v[32:35], v[28:31], v[14:17]
	v_mfma_f32_16x16x32_bf16 v[2:5], v[46:49], v[28:31], v[2:5]
	v_mfma_f32_16x16x32_bf16 v[20:23], v[36:39], v[28:31], v[20:23]
	v_mfma_f32_16x16x32_bf16 v[24:27], v[42:45], v[28:31], v[24:27]
	s_waitcnt lgkmcnt(0)
	v_mfma_f32_16x16x32_bf16 v[14:17], v[54:57], v[50:53], v[14:17]
	v_mfma_f32_16x16x32_bf16 v[2:5], v[10:13], v[50:53], v[2:5]
	v_mfma_f32_16x16x32_bf16 v[20:23], v[58:61], v[50:53], v[20:23]
	v_mfma_f32_16x16x32_bf16 v[24:27], v[62:65], v[50:53], v[24:27]
	s_waitcnt vmcnt(0)
	v_and_b32_e32 v0, 15, v18
	v_bfe_u32 v41, v18, 4, 2
	s_barrier
	ds_read_b128 v[10:13], v9 offset:0
	ds_read_b128 v[28:31], v8 offset:0
	ds_read_b128 v[32:35], v8 offset:2048
	ds_read_b128 v[36:39], v8 offset:4096
	ds_read_b128 v[42:45], v8 offset:6144
	ds_read_b128 v[46:49], v9 offset:1024
	ds_read_b128 v[50:53], v8 offset:1024
	ds_read_b128 v[54:57], v8 offset:3072
	ds_read_b128 v[58:61], v8 offset:5120
	ds_read_b128 v[62:65], v8 offset:7168
	s_waitcnt lgkmcnt(5)
	s_nop 0
	v_mfma_f32_16x16x32_bf16 v[6:9], v[28:31], v[10:13], v[14:17]
	v_mfma_f32_16x16x32_bf16 v[2:5], v[42:45], v[10:13], v[2:5]
	v_mfma_f32_16x16x32_bf16 v[20:23], v[32:35], v[10:13], v[20:23]
	v_mfma_f32_16x16x32_bf16 v[24:27], v[36:39], v[10:13], v[24:27]
	s_waitcnt lgkmcnt(0)
	v_mfma_f32_16x16x32_bf16 v[14:17], v[50:53], v[46:49], v[6:9]
	v_mfma_f32_16x16x32_bf16 v[10:13], v[54:57], v[46:49], v[20:23]
	v_mfma_f32_16x16x32_bf16 v[6:9], v[58:61], v[46:49], v[24:27]
	v_mfma_f32_16x16x32_bf16 v[2:5], v[62:65], v[46:49], v[2:5]
	v_ashrrev_i32_e32 v19, 3, v18
	v_and_b32_e32 v42, -16, v19
	s_cmp_gt_i32 s19, 7
	s_mov_b64 s[4:5], -1
	v_readlane_b32 s1, v215, 34
	s_cbranch_scc0 .LBB0_369
	s_cmp_gt_u32 s19, 15
	s_cbranch_scc0 .LBB0_364
	s_cmpk_gt_i32 s0, 0xfff
	s_cselect_b64 s[4:5], -1, 0
	s_addk_i32 s8, 0xf000
	s_lshr_b32 s1, s8, 10
	s_cmpk_lt_i32 s0, 0x1000
	s_cselect_b64 s[6:7], -1, 0
	s_and_b64 s[8:9], s[6:7], exec
	s_movk_i32 s8, 0x3c0
	s_cselect_b32 s8, 0xc0, s8
	s_and_b32 s8, s8, s0
	v_add_u32_e32 v18, s8, v42
	s_cmp_gt_u32 s19, 31
	s_mov_b64 s[8:9], -1
	s_cbranch_scc0 .LBB0_349
	s_cmp_gt_u32 s19, 39
	s_cbranch_scc0 .LBB0_342
	v_add_u32_e32 v20, s0, v42
	v_mul_f32_e32 v24, 0xbfb8aa3b, v14
	v_mul_f32_e32 v25, 0xbfb8aa3b, v15
	v_mul_f32_e32 v26, 0xbfb8aa3b, v16
	v_mul_f32_e32 v27, 0xbfb8aa3b, v17
	v_or_b32_e32 v20, v20, v0
	v_exp_f32_e32 v24, v24
	v_exp_f32_e32 v25, v25
	v_exp_f32_e32 v26, v26
	v_exp_f32_e32 v27, v27
	v_ashrrev_i32_e32 v21, 31, v20
	v_lshlrev_b64 v[20:21], 12, v[20:21]
	v_lshl_add_u64 v[20:21], s[48:49], 0, v[20:21]
	v_lshl_add_u64 v[20:21], s[2:3], 1, v[20:21]
	v_lshlrev_b32_e32 v22, 7, v40
	v_mov_b32_e32 v23, v1
	v_add_f32_e32 v24, 1.0, v24
	v_add_f32_e32 v25, 1.0, v25
	v_add_f32_e32 v26, 1.0, v26
	v_add_f32_e32 v27, 1.0, v27
	v_lshl_add_u64 v[20:21], v[20:21], 0, v[22:23]
	v_lshlrev_b32_e32 v22, 3, v41
	v_rcp_f32_e32 v24, v24
	v_rcp_f32_e32 v25, v25
	v_rcp_f32_e32 v26, v26
	v_rcp_f32_e32 v27, v27
	v_lshl_add_u64 v[22:23], v[20:21], 0, v[22:23]
	s_mov_b64 s[8:9], 0xa15d800
	v_lshl_add_u64 v[20:21], v[22:23], 0, s[8:9]
	s_mov_b32 s8, 0xa15d000
	v_add_co_u32_e32 v22, vcc, s8, v22
	v_cvt_pk_bf16_f32 v24, v24, v25
	v_cvt_pk_bf16_f32 v25, v26, v27
	v_addc_co_u32_e32 v23, vcc, 0, v23, vcc
	global_store_dwordx2 v[22:23], v[24:25], off offset:2048
	v_mul_f32_e32 v22, 0xbfb8aa3b, v10
	v_mul_f32_e32 v23, 0xbfb8aa3b, v11
	v_mul_f32_e32 v24, 0xbfb8aa3b, v12
	v_mul_f32_e32 v25, 0xbfb8aa3b, v13
	v_exp_f32_e32 v22, v22
	v_exp_f32_e32 v23, v23
	v_exp_f32_e32 v24, v24
	v_exp_f32_e32 v25, v25
	v_add_f32_e32 v22, 1.0, v22
	v_add_f32_e32 v23, 1.0, v23
	v_add_f32_e32 v24, 1.0, v24
	v_add_f32_e32 v25, 1.0, v25
	v_rcp_f32_e32 v22, v22
	v_rcp_f32_e32 v23, v23
	v_rcp_f32_e32 v24, v24
	v_rcp_f32_e32 v25, v25
	s_mov_b64 s[8:9], 0
	v_cvt_pk_bf16_f32 v22, v22, v23
	v_cvt_pk_bf16_f32 v23, v24, v25
	global_store_dwordx2 v[20:21], v[22:23], off offset:32
	v_mul_f32_e32 v22, 0xbfb8aa3b, v6
	v_mul_f32_e32 v23, 0xbfb8aa3b, v7
	v_mul_f32_e32 v24, 0xbfb8aa3b, v8
	v_mul_f32_e32 v25, 0xbfb8aa3b, v9
	v_exp_f32_e32 v22, v22
	v_exp_f32_e32 v23, v23
	v_exp_f32_e32 v24, v24
	v_exp_f32_e32 v25, v25
	v_add_f32_e32 v22, 1.0, v22
	v_add_f32_e32 v23, 1.0, v23
	v_add_f32_e32 v24, 1.0, v24
	v_add_f32_e32 v25, 1.0, v25
	v_rcp_f32_e32 v22, v22
	v_rcp_f32_e32 v23, v23
	v_rcp_f32_e32 v24, v24
	v_rcp_f32_e32 v25, v25
	v_cvt_pk_bf16_f32 v22, v22, v23
	v_cvt_pk_bf16_f32 v23, v24, v25
	global_store_dwordx2 v[20:21], v[22:23], off offset:64
	v_mul_f32_e32 v22, 0xbfb8aa3b, v2
	v_mul_f32_e32 v23, 0xbfb8aa3b, v3
	v_mul_f32_e32 v24, 0xbfb8aa3b, v4
	v_mul_f32_e32 v25, 0xbfb8aa3b, v5
	v_exp_f32_e32 v22, v22
	v_exp_f32_e32 v23, v23
	v_exp_f32_e32 v24, v24
	v_exp_f32_e32 v25, v25
	v_add_f32_e32 v22, 1.0, v22
	v_add_f32_e32 v23, 1.0, v23
	v_add_f32_e32 v24, 1.0, v24
	v_add_f32_e32 v25, 1.0, v25
	v_rcp_f32_e32 v22, v22
	v_rcp_f32_e32 v23, v23
	v_rcp_f32_e32 v24, v24
	v_rcp_f32_e32 v25, v25
	v_cvt_pk_bf16_f32 v22, v22, v23
	v_cvt_pk_bf16_f32 v23, v24, v25
	global_store_dwordx2 v[20:21], v[22:23], off offset:96

.LBB0_372:
	s_andn2_b64 vcc, exec, s[0:1]
	s_cbranch_vccnz .LBB0_397
	v_readlane_b32 s4, v217, 0
	v_readlane_b32 s5, v214, 57
	v_readlane_b32 s38, v217, 1
	v_readlane_b32 s39, v217, 2
	v_lshrrev_b32_e32 v197, 6, v142
	s_sub_u32 s38, s38, 0xd0
	s_subb_u32 s39, s39, 0
	v_readfirstlane_b32 s6, v197
	s_load_dwordx2 s[38:39], s[38:39], 0x40
	v_and_b32_e32 v194, 63, v142
	v_and_b32_e32 v195, 7, v194
	v_lshlrev_b32_e32 v195, 3, v195
	v_lshrrev_b32_e32 v197, 3, v194
	v_lshl_add_u32 v195, v197, 10, v195
	v_lshlrev_b32_e32 v194, 4, v194
	v_mov_b32_e32 v196, 0x358637bd
	s_lshr_b32 s7, s4, 3
	s_lshl_b32 s7, s7, 3
	s_add_u32 s7, s7, s6
	s_and_b32 s10, s4, 7
	s_mul_i32 s10, s10, 192
	s_add_u32 s11, s7, 0
	s_mul_i32 s12, s11, 43691
	s_lshr_b32 s12, s12, 23
	s_mul_i32 s12, s12, 1344
	s_add_u32 s11, s11, s12
	s_add_u32 s98, s11, s10
	s_add_u32 s11, s7, 256
	s_mul_i32 s12, s11, 43691
	s_lshr_b32 s12, s12, 23
	s_mul_i32 s12, s12, 1344
	s_add_u32 s11, s11, s12
	s_add_u32 s99, s11, s10
	s_add_u32 s11, s7, 512
	s_mul_i32 s12, s11, 43691
	s_lshr_b32 s12, s12, 23
	s_mul_i32 s12, s12, 1344
	s_add_u32 s11, s11, s12
	s_add_u32 s17, s11, s10
	s_waitcnt lgkmcnt(0)
	s_lshl_b32 s11, s98, 12
	s_add_u32 s68, s48, s11
	s_addc_u32 s69, s49, 0
	global_load_dwordx4 v[2:5], v194, s[68:69] offset:0
	global_load_dwordx4 v[6:9], v194, s[68:69] offset:1024
	global_load_dwordx4 v[10:13], v194, s[68:69] offset:2048
	global_load_dwordx4 v[14:17], v194, s[68:69] offset:3072
	s_lshl_b32 s11, s99, 12
	s_add_u32 s70, s48, s11
	s_addc_u32 s71, s49, 0
	global_load_dwordx4 v[18:21], v194, s[70:71] offset:0
	global_load_dwordx4 v[22:25], v194, s[70:71] offset:1024
	global_load_dwordx4 v[26:29], v194, s[70:71] offset:2048
	global_load_dwordx4 v[30:33], v194, s[70:71] offset:3072
	s_lshl_b32 s11, s17, 12
	s_add_u32 s72, s48, s11
	s_addc_u32 s73, s49, 0
	global_load_dwordx4 v[34:37], v194, s[72:73] offset:0
	global_load_dwordx4 v[38:41], v194, s[72:73] offset:1024
	global_load_dwordx4 v[42:45], v194, s[72:73] offset:2048
	global_load_dwordx4 v[46:49], v194, s[72:73] offset:3072
	s_mov_b32 s42, s17
	s_mul_i32 s11, s5, 3
	s_add_u32 s11, s11, 1
	s_lshl_b32 s11, s11, 12
	s_add_u32 s38, s38, s11
	s_addc_u32 s39, s39, 0
	global_load_dwordx4 v[50:53], v194, s[38:39] offset:0
	global_load_dwordx4 v[54:57], v194, s[38:39] offset:1024
	global_load_dwordx4 v[58:61], v194, s[38:39] offset:2048
	global_load_dwordx4 v[62:65], v194, s[38:39] offset:3072
	s_sub_u32 s11, s98, 0x1000
	s_lshr_b32 s11, s11, 10
	s_add_u32 s11, s11, 1
	s_cmp_lt_u32 s98, 0x1000
	s_cselect_b32 s11, 0, s11
	s_mul_i32 s12, s5, 3
	s_add_u32 s11, s11, s12
	s_mul_i32 s11, s11, 0x9000
	s_add_u32 s11, s11, 0x3000
	s_add_u32 s74, s34, s11
	s_addc_u32 s75, s35, 0
	s_add_u32 s80, s74, 0x1000
	s_addc_u32 s81, s75, 0
	global_load_dwordx4 v[66:69], v194, s[74:75] offset:0
	global_load_dwordx4 v[70:73], v194, s[74:75] offset:1024
	global_load_dwordx4 v[74:77], v194, s[74:75] offset:2048
	global_load_dwordx4 v[78:81], v194, s[74:75] offset:3072
	global_load_dwordx4 v[114:117], v194, s[80:81] offset:0
	global_load_dwordx4 v[118:121], v194, s[80:81] offset:1024
	global_load_dwordx4 v[122:125], v194, s[80:81] offset:2048
	global_load_dwordx4 v[126:129], v194, s[80:81] offset:3072
	s_sub_u32 s11, s99, 0x1000
	s_lshr_b32 s11, s11, 10
	s_add_u32 s11, s11, 1
	s_cmp_lt_u32 s99, 0x1000
	s_cselect_b32 s11, 0, s11
	s_mul_i32 s12, s5, 3
	s_add_u32 s11, s11, s12
	s_mul_i32 s11, s11, 0x9000
	s_add_u32 s11, s11, 0x3000
	s_add_u32 s76, s34, s11
	s_addc_u32 s77, s35, 0
	s_add_u32 s82, s76, 0x1000
	s_addc_u32 s83, s77, 0
	global_load_dwordx4 v[82:85], v194, s[76:77] offset:0
	global_load_dwordx4 v[86:89], v194, s[76:77] offset:1024
	global_load_dwordx4 v[90:93], v194, s[76:77] offset:2048
	global_load_dwordx4 v[94:97], v194, s[76:77] offset:3072
	global_load_dwordx4 v[162:165], v194, s[82:83] offset:0
	global_load_dwordx4 v[166:169], v194, s[82:83] offset:1024
	global_load_dwordx4 v[170:173], v194, s[82:83] offset:2048
	global_load_dwordx4 v[174:177], v194, s[82:83] offset:3072
	s_sub_u32 s11, s42, 0x1000
	s_lshr_b32 s11, s11, 10
	s_add_u32 s11, s11, 1
	s_cmp_lt_u32 s42, 0x1000
	s_cselect_b32 s11, 0, s11
	s_mul_i32 s12, s5, 3
	s_add_u32 s11, s11, s12
	s_mul_i32 s11, s11, 0x9000
	s_add_u32 s11, s11, 0x3000
	s_add_u32 s78, s34, s11
	s_addc_u32 s79, s35, 0
	s_add_u32 s92, s78, 0x1000
	s_addc_u32 s93, s79, 0
	global_load_dwordx4 v[98:101], v194, s[78:79] offset:0
	global_load_dwordx4 v[102:105], v194, s[78:79] offset:1024
	global_load_dwordx4 v[106:109], v194, s[78:79] offset:2048
	global_load_dwordx4 v[110:113], v194, s[78:79] offset:3072
	global_load_dwordx4 v[178:181], v194, s[92:93] offset:0
	global_load_dwordx4 v[182:185], v194, s[92:93] offset:1024
	global_load_dwordx4 v[186:189], v194, s[92:93] offset:2048
	global_load_dwordx4 v[190:193], v194, s[92:93] offset:3072
	s_waitcnt vmcnt(28)
	s_lshr_b32 s11, s98, 4
	s_lshl_b32 s11, s11, 15
	s_and_b32 s12, s98, 15
	s_lshl_b32 s12, s12, 6
	s_add_u32 s11, s11, s12
	s_add_u32 s68, s24, s11
	s_addc_u32 s69, s25, 0
	s_lshr_b32 s11, s99, 4
	s_lshl_b32 s11, s11, 15
	s_and_b32 s12, s99, 15
	s_lshl_b32 s12, s12, 6
	s_add_u32 s11, s11, s12
	s_add_u32 s70, s24, s11
	s_addc_u32 s71, s25, 0
	s_lshr_b32 s11, s42, 4
	s_lshl_b32 s11, s11, 15
	s_and_b32 s12, s42, 15
	s_lshl_b32 s12, s12, 6
	s_add_u32 s11, s11, s12
	s_add_u32 s72, s24, s11
	s_addc_u32 s73, s25, 0
	v_mul_f32_e32 v198, v2, v2
	v_mul_f32_e32 v199, v18, v18
	v_mul_f32_e32 v200, v34, v34
	v_fmac_f32_e32 v198, v3, v3
	v_fmac_f32_e32 v199, v19, v19
	v_fmac_f32_e32 v200, v35, v35
	v_fmac_f32_e32 v198, v4, v4
	v_fmac_f32_e32 v199, v20, v20
	v_fmac_f32_e32 v200, v36, v36
	v_fmac_f32_e32 v198, v5, v5
	v_fmac_f32_e32 v199, v21, v21
	v_fmac_f32_e32 v200, v37, v37
	v_fmac_f32_e32 v198, v6, v6
	v_fmac_f32_e32 v199, v22, v22
	v_fmac_f32_e32 v200, v38, v38
	v_fmac_f32_e32 v198, v7, v7
	v_fmac_f32_e32 v199, v23, v23
	v_fmac_f32_e32 v200, v39, v39
	v_fmac_f32_e32 v198, v8, v8
	v_fmac_f32_e32 v199, v24, v24
	v_fmac_f32_e32 v200, v40, v40
	v_fmac_f32_e32 v198, v9, v9
	v_fmac_f32_e32 v199, v25, v25
	v_fmac_f32_e32 v200, v41, v41
	v_fmac_f32_e32 v198, v10, v10
	v_fmac_f32_e32 v199, v26, v26
	v_fmac_f32_e32 v200, v42, v42
	v_fmac_f32_e32 v198, v11, v11
	v_fmac_f32_e32 v199, v27, v27
	v_fmac_f32_e32 v200, v43, v43
	v_fmac_f32_e32 v198, v12, v12
	v_fmac_f32_e32 v199, v28, v28
	v_fmac_f32_e32 v200, v44, v44
	v_fmac_f32_e32 v198, v13, v13
	v_fmac_f32_e32 v199, v29, v29
	v_fmac_f32_e32 v200, v45, v45
	v_fmac_f32_e32 v198, v14, v14
	v_fmac_f32_e32 v199, v30, v30
	v_fmac_f32_e32 v200, v46, v46
	v_fmac_f32_e32 v198, v15, v15
	v_fmac_f32_e32 v199, v31, v31
	v_fmac_f32_e32 v200, v47, v47
	v_fmac_f32_e32 v198, v16, v16
	v_fmac_f32_e32 v199, v32, v32
	v_fmac_f32_e32 v200, v48, v48
	v_fmac_f32_e32 v198, v17, v17
	v_fmac_f32_e32 v199, v33, v33
	v_fmac_f32_e32 v200, v49, v49
	s_nop 1
	v_add_f32_dpp v198, v198, v198 quad_perm:[1,0,3,2] row_mask:0xf bank_mask:0xf
	v_add_f32_dpp v199, v199, v199 quad_perm:[1,0,3,2] row_mask:0xf bank_mask:0xf
	v_add_f32_dpp v200, v200, v200 quad_perm:[1,0,3,2] row_mask:0xf bank_mask:0xf
	s_nop 1
	v_add_f32_dpp v198, v198, v198 quad_perm:[2,3,0,1] row_mask:0xf bank_mask:0xf
	v_add_f32_dpp v199, v199, v199 quad_perm:[2,3,0,1] row_mask:0xf bank_mask:0xf
	v_add_f32_dpp v200, v200, v200 quad_perm:[2,3,0,1] row_mask:0xf bank_mask:0xf
	s_nop 1
	v_add_f32_dpp v198, v198, v198 row_half_mirror row_mask:0xf bank_mask:0xf
	v_add_f32_dpp v199, v199, v199 row_half_mirror row_mask:0xf bank_mask:0xf
	v_add_f32_dpp v200, v200, v200 row_half_mirror row_mask:0xf bank_mask:0xf
	s_nop 1
	v_add_f32_dpp v198, v198, v198 row_mirror row_mask:0xf bank_mask:0xf
	v_add_f32_dpp v199, v199, v199 row_mirror row_mask:0xf bank_mask:0xf
	v_add_f32_dpp v200, v200, v200 row_mirror row_mask:0xf bank_mask:0xf
	s_nop 1
	v_add_f32_dpp v198, v198, v198 row_bcast:15 row_mask:0xa bank_mask:0xf
	v_add_f32_dpp v199, v199, v199 row_bcast:15 row_mask:0xa bank_mask:0xf
	v_add_f32_dpp v200, v200, v200 row_bcast:15 row_mask:0xa bank_mask:0xf
	s_nop 1
	v_add_f32_dpp v198, v198, v198 row_bcast:31 row_mask:0xc bank_mask:0xf
	v_add_f32_dpp v199, v199, v199 row_bcast:31 row_mask:0xc bank_mask:0xf
	v_add_f32_dpp v200, v200, v200 row_bcast:31 row_mask:0xc bank_mask:0xf
	s_nop 1
	v_readlane_b32 s32, v198, 63
	v_readlane_b32 s20, v199, 63
	v_readlane_b32 s94, v200, 63
	s_nop 0
	v_mov_b32_e32 v201, s32
	v_mov_b32_e32 v202, s20
	v_mov_b32_e32 v203, s94
	v_fmamk_f32 v201, v201, 0x3a800000, v196
	v_fmamk_f32 v202, v202, 0x3a800000, v196
	v_fmamk_f32 v203, v203, 0x3a800000, v196
	v_rsq_f32_e32 v201, v201
	v_rsq_f32_e32 v202, v202
	v_rsq_f32_e32 v203, v203
	s_waitcnt vmcnt(0)
	v_mul_f32_e32 v204, v2, v201
	v_mul_f32_e32 v205, v3, v201
	v_mul_f32_e32 v206, v4, v201
	v_mul_f32_e32 v207, v5, v201
	v_mul_f32_e32 v204, v50, v204
	v_mul_f32_e32 v205, v51, v205
	v_mul_f32_e32 v206, v52, v206
	v_mul_f32_e32 v207, v53, v207
	v_add_f32_e32 v114, 1.0, v114
	v_add_f32_e32 v115, 1.0, v115
	v_add_f32_e32 v116, 1.0, v116
	v_add_f32_e32 v117, 1.0, v117
	v_fma_f32 v204, v114, v204, v66
	v_fma_f32 v205, v115, v205, v67
	v_fma_f32 v206, v116, v206, v68
	v_fma_f32 v207, v117, v207, v69
	v_cvt_pk_bf16_f32 v208, v204, v205
	v_cvt_pk_bf16_f32 v209, v206, v207
	s_add_u32 s14, s68, 0x0
	s_addc_u32 s15, s69, 0
	global_store_dwordx2 v195, v[208:209], s[14:15]
	v_mul_f32_e32 v204, v6, v201
	v_mul_f32_e32 v205, v7, v201
	v_mul_f32_e32 v206, v8, v201
	v_mul_f32_e32 v207, v9, v201
	v_mul_f32_e32 v204, v54, v204
	v_mul_f32_e32 v205, v55, v205
	v_mul_f32_e32 v206, v56, v206
	v_mul_f32_e32 v207, v57, v207
	v_add_f32_e32 v118, 1.0, v118
	v_add_f32_e32 v119, 1.0, v119
	v_add_f32_e32 v120, 1.0, v120
	v_add_f32_e32 v121, 1.0, v121
	v_fma_f32 v204, v118, v204, v70
	v_fma_f32 v205, v119, v205, v71
	v_fma_f32 v206, v120, v206, v72
	v_fma_f32 v207, v121, v207, v73
	v_cvt_pk_bf16_f32 v210, v204, v205
	v_cvt_pk_bf16_f32 v211, v206, v207
	s_add_u32 s14, s68, 0x2000
	s_addc_u32 s15, s69, 0
	global_store_dwordx2 v195, v[210:211], s[14:15]
	v_mul_f32_e32 v204, v10, v201
	v_mul_f32_e32 v205, v11, v201
	v_mul_f32_e32 v206, v12, v201
	v_mul_f32_e32 v207, v13, v201
	v_mul_f32_e32 v204, v58, v204
	v_mul_f32_e32 v205, v59, v205
	v_mul_f32_e32 v206, v60, v206
	v_mul_f32_e32 v207, v61, v207
	v_add_f32_e32 v122, 1.0, v122
	v_add_f32_e32 v123, 1.0, v123
	v_add_f32_e32 v124, 1.0, v124
	v_add_f32_e32 v125, 1.0, v125
	v_fma_f32 v204, v122, v204, v74
	v_fma_f32 v205, v123, v205, v75
	v_fma_f32 v206, v124, v206, v76
	v_fma_f32 v207, v125, v207, v77
	v_cvt_pk_bf16_f32 v208, v204, v205
	v_cvt_pk_bf16_f32 v209, v206, v207
	s_add_u32 s14, s68, 0x4000
	s_addc_u32 s15, s69, 0
	global_store_dwordx2 v195, v[208:209], s[14:15]
	v_mul_f32_e32 v204, v14, v201
	v_mul_f32_e32 v205, v15, v201
	v_mul_f32_e32 v206, v16, v201
	v_mul_f32_e32 v207, v17, v201
	v_mul_f32_e32 v204, v62, v204
	v_mul_f32_e32 v205, v63, v205
	v_mul_f32_e32 v206, v64, v206
	v_mul_f32_e32 v207, v65, v207
	v_add_f32_e32 v126, 1.0, v126
	v_add_f32_e32 v127, 1.0, v127
	v_add_f32_e32 v128, 1.0, v128
	v_add_f32_e32 v129, 1.0, v129
	v_fma_f32 v204, v126, v204, v78
	v_fma_f32 v205, v127, v205, v79
	v_fma_f32 v206, v128, v206, v80
	v_fma_f32 v207, v129, v207, v81
	v_cvt_pk_bf16_f32 v210, v204, v205
	v_cvt_pk_bf16_f32 v211, v206, v207
	s_add_u32 s14, s68, 0x6000
	s_addc_u32 s15, s69, 0
	global_store_dwordx2 v195, v[210:211], s[14:15]
	v_mul_f32_e32 v204, v18, v202
	v_mul_f32_e32 v205, v19, v202
	v_mul_f32_e32 v206, v20, v202
	v_mul_f32_e32 v207, v21, v202
	v_mul_f32_e32 v204, v50, v204
	v_mul_f32_e32 v205, v51, v205
	v_mul_f32_e32 v206, v52, v206
	v_mul_f32_e32 v207, v53, v207
	v_add_f32_e32 v162, 1.0, v162
	v_add_f32_e32 v163, 1.0, v163
	v_add_f32_e32 v164, 1.0, v164
	v_add_f32_e32 v165, 1.0, v165
	v_fma_f32 v204, v162, v204, v82
	v_fma_f32 v205, v163, v205, v83
	v_fma_f32 v206, v164, v206, v84
	v_fma_f32 v207, v165, v207, v85
	v_cvt_pk_bf16_f32 v208, v204, v205
	v_cvt_pk_bf16_f32 v209, v206, v207
	s_add_u32 s14, s70, 0x0
	s_addc_u32 s15, s71, 0
	global_store_dwordx2 v195, v[208:209], s[14:15]
	v_mul_f32_e32 v204, v22, v202
	v_mul_f32_e32 v205, v23, v202
	v_mul_f32_e32 v206, v24, v202
	v_mul_f32_e32 v207, v25, v202
	v_mul_f32_e32 v204, v54, v204
	v_mul_f32_e32 v205, v55, v205
	v_mul_f32_e32 v206, v56, v206
	v_mul_f32_e32 v207, v57, v207
	v_add_f32_e32 v166, 1.0, v166
	v_add_f32_e32 v167, 1.0, v167
	v_add_f32_e32 v168, 1.0, v168
	v_add_f32_e32 v169, 1.0, v169
	v_fma_f32 v204, v166, v204, v86
	v_fma_f32 v205, v167, v205, v87
	v_fma_f32 v206, v168, v206, v88
	v_fma_f32 v207, v169, v207, v89
	v_cvt_pk_bf16_f32 v210, v204, v205
	v_cvt_pk_bf16_f32 v211, v206, v207
	s_add_u32 s14, s70, 0x2000
	s_addc_u32 s15, s71, 0
	global_store_dwordx2 v195, v[210:211], s[14:15]
	v_mul_f32_e32 v204, v26, v202
	v_mul_f32_e32 v205, v27, v202
	v_mul_f32_e32 v206, v28, v202
	v_mul_f32_e32 v207, v29, v202
	v_mul_f32_e32 v204, v58, v204
	v_mul_f32_e32 v205, v59, v205
	v_mul_f32_e32 v206, v60, v206
	v_mul_f32_e32 v207, v61, v207
	v_add_f32_e32 v170, 1.0, v170
	v_add_f32_e32 v171, 1.0, v171
	v_add_f32_e32 v172, 1.0, v172
	v_add_f32_e32 v173, 1.0, v173
	v_fma_f32 v204, v170, v204, v90
	v_fma_f32 v205, v171, v205, v91
	v_fma_f32 v206, v172, v206, v92
	v_fma_f32 v207, v173, v207, v93
	v_cvt_pk_bf16_f32 v208, v204, v205
	v_cvt_pk_bf16_f32 v209, v206, v207
	s_add_u32 s14, s70, 0x4000
	s_addc_u32 s15, s71, 0
	global_store_dwordx2 v195, v[208:209], s[14:15]
	v_mul_f32_e32 v204, v30, v202
	v_mul_f32_e32 v205, v31, v202
	v_mul_f32_e32 v206, v32, v202
	v_mul_f32_e32 v207, v33, v202
	v_mul_f32_e32 v204, v62, v204
	v_mul_f32_e32 v205, v63, v205
	v_mul_f32_e32 v206, v64, v206
	v_mul_f32_e32 v207, v65, v207
	v_add_f32_e32 v174, 1.0, v174
	v_add_f32_e32 v175, 1.0, v175
	v_add_f32_e32 v176, 1.0, v176
	v_add_f32_e32 v177, 1.0, v177
	v_fma_f32 v204, v174, v204, v94
	v_fma_f32 v205, v175, v205, v95
	v_fma_f32 v206, v176, v206, v96
	v_fma_f32 v207, v177, v207, v97
	v_cvt_pk_bf16_f32 v210, v204, v205
	v_cvt_pk_bf16_f32 v211, v206, v207
	s_add_u32 s14, s70, 0x6000
	s_addc_u32 s15, s71, 0
	global_store_dwordx2 v195, v[210:211], s[14:15]
	v_mul_f32_e32 v204, v34, v203
	v_mul_f32_e32 v205, v35, v203
	v_mul_f32_e32 v206, v36, v203
	v_mul_f32_e32 v207, v37, v203
	v_mul_f32_e32 v204, v50, v204
	v_mul_f32_e32 v205, v51, v205
	v_mul_f32_e32 v206, v52, v206
	v_mul_f32_e32 v207, v53, v207
	v_add_f32_e32 v178, 1.0, v178
	v_add_f32_e32 v179, 1.0, v179
	v_add_f32_e32 v180, 1.0, v180
	v_add_f32_e32 v181, 1.0, v181
	v_fma_f32 v204, v178, v204, v98
	v_fma_f32 v205, v179, v205, v99
	v_fma_f32 v206, v180, v206, v100
	v_fma_f32 v207, v181, v207, v101
	v_cvt_pk_bf16_f32 v208, v204, v205
	v_cvt_pk_bf16_f32 v209, v206, v207
	s_add_u32 s14, s72, 0x0
	s_addc_u32 s15, s73, 0
	global_store_dwordx2 v195, v[208:209], s[14:15]
	v_mul_f32_e32 v204, v38, v203
	v_mul_f32_e32 v205, v39, v203
	v_mul_f32_e32 v206, v40, v203
	v_mul_f32_e32 v207, v41, v203
	v_mul_f32_e32 v204, v54, v204
	v_mul_f32_e32 v205, v55, v205
	v_mul_f32_e32 v206, v56, v206
	v_mul_f32_e32 v207, v57, v207
	v_add_f32_e32 v182, 1.0, v182
	v_add_f32_e32 v183, 1.0, v183
	v_add_f32_e32 v184, 1.0, v184
	v_add_f32_e32 v185, 1.0, v185
	v_fma_f32 v204, v182, v204, v102
	v_fma_f32 v205, v183, v205, v103
	v_fma_f32 v206, v184, v206, v104
	v_fma_f32 v207, v185, v207, v105
	v_cvt_pk_bf16_f32 v210, v204, v205
	v_cvt_pk_bf16_f32 v211, v206, v207
	s_add_u32 s14, s72, 0x2000
	s_addc_u32 s15, s73, 0
	global_store_dwordx2 v195, v[210:211], s[14:15]
	v_mul_f32_e32 v204, v42, v203
	v_mul_f32_e32 v205, v43, v203
	v_mul_f32_e32 v206, v44, v203
	v_mul_f32_e32 v207, v45, v203
	v_mul_f32_e32 v204, v58, v204
	v_mul_f32_e32 v205, v59, v205
	v_mul_f32_e32 v206, v60, v206
	v_mul_f32_e32 v207, v61, v207
	v_add_f32_e32 v186, 1.0, v186
	v_add_f32_e32 v187, 1.0, v187
	v_add_f32_e32 v188, 1.0, v188
	v_add_f32_e32 v189, 1.0, v189
	v_fma_f32 v204, v186, v204, v106
	v_fma_f32 v205, v187, v205, v107
	v_fma_f32 v206, v188, v206, v108
	v_fma_f32 v207, v189, v207, v109
	v_cvt_pk_bf16_f32 v208, v204, v205
	v_cvt_pk_bf16_f32 v209, v206, v207
	s_add_u32 s14, s72, 0x4000
	s_addc_u32 s15, s73, 0
	global_store_dwordx2 v195, v[208:209], s[14:15]
	v_mul_f32_e32 v204, v46, v203
	v_mul_f32_e32 v205, v47, v203
	v_mul_f32_e32 v206, v48, v203
	v_mul_f32_e32 v207, v49, v203
	v_mul_f32_e32 v204, v62, v204
	v_mul_f32_e32 v205, v63, v205
	v_mul_f32_e32 v206, v64, v206
	v_mul_f32_e32 v207, v65, v207
	v_add_f32_e32 v190, 1.0, v190
	v_add_f32_e32 v191, 1.0, v191
	v_add_f32_e32 v192, 1.0, v192
	v_add_f32_e32 v193, 1.0, v193
	v_fma_f32 v204, v190, v204, v110
	v_fma_f32 v205, v191, v205, v111
	v_fma_f32 v206, v192, v206, v112
	v_fma_f32 v207, v193, v207, v113
	v_cvt_pk_bf16_f32 v210, v204, v205
	v_cvt_pk_bf16_f32 v211, v206, v207
	s_add_u32 s14, s72, 0x6000
	s_addc_u32 s15, s73, 0
	global_store_dwordx2 v195, v[210:211], s[14:15]
	s_branch .LBB0_397

.LBB0_466:
	s_or_b64 exec, exec, s[0:1]
	v_cmp_eq_u32_e32 vcc, 0x1600, v11
	s_nop 1
	v_cndmask_b32_e64 v166, 0, 1, vcc
	v_cmp_eq_u32_e32 vcc, 0xb00, v4
	s_nop 1
	v_cndmask_b32_e64 v166, v166, 1, vcc
	v_cmp_eq_u32_e32 vcc, 0x1c00, v11
	s_nop 1
	v_cndmask_b32_e64 v166, v166, 1, vcc
	v_lshlrev_b32_e32 v173, 5, v4
	v_mul_i32_i24_e32 v14, v4, v10
	v_mad_u64_u32 v[14:15], s[0:1], v14, v11, 0
	v_mul_hi_i32_i24_e32 v13, v4, v10
	v_mov_b32_e32 v38, v15
	v_mad_u64_u32 v[38:39], s[0:1], v13, v11, v[38:39]
	v_mov_b32_e32 v15, v38
	v_lshl_add_u64 v[6:7], v[14:15], 2, v[6:7]
	v_lshlrev_b32_sdwa v14, v159, sext(v9) dst_sel:DWORD dst_unused:UNUSED_PAD src0_sel:DWORD src1_sel:WORD_0
	v_bfe_u32 v13, v5, 4, 4
	v_ashrrev_i32_e32 v9, 31, v8
	v_or_b32_e32 v15, v13, v14
	v_lshl_add_u64 v[46:47], v[8:9], 2, v[6:7]
	v_or_b32_e32 v8, 16, v15
	v_mul_hi_i32_i24_e32 v7, v15, v11
	v_mul_i32_i24_e32 v6, v15, v11
	v_mul_hi_i32_i24_e32 v9, v8, v11
	v_mul_i32_i24_e32 v8, v8, v11
	v_lshl_add_u64 v[6:7], v[6:7], 2, v[46:47]
	v_lshl_add_u64 v[38:39], v[8:9], 2, v[46:47]
	s_waitcnt vmcnt(0)
	s_barrier
	global_load_dwordx4 v[6:9], v[6:7], off nt
	s_nop 0
	global_load_dwordx4 v[38:41], v[38:39], off nt
	v_or_b32_e32 v37, 32, v15
	v_mul_hi_i32_i24_e32 v43, v37, v11
	v_mul_i32_i24_e32 v42, v37, v11
	v_lshl_add_u64 v[42:43], v[42:43], 2, v[46:47]
	v_or_b32_e32 v15, 48, v15
	global_load_dwordx4 v[42:45], v[42:43], off nt
	v_mul_hi_i32_i24_e32 v49, v15, v11
	v_mul_i32_i24_e32 v48, v15, v11
	v_lshl_add_u64 v[46:47], v[48:49], 2, v[46:47]
	global_load_dwordx4 v[46:49], v[46:47], off nt
	v_readlane_b32 s0, v217, 7
	v_readlane_b32 s1, v217, 8
	v_lshrrev_b32_e32 v15, 8, v5
	v_bfe_u32 v37, v5, 2, 6
	v_mov_b64_e32 v[50:51], s[0:1]
	s_mov_b32 s0, 0x3500000
	v_mad_i64_i32 v[10:11], s[0:1], v10, s0, v[50:51]
	v_lshlrev_b32_e32 v52, 4, v5
	s_movk_i32 s0, 0x4100
	v_lshlrev_b32_e32 v12, 2, v12
	v_and_b32_e32 v53, 0xfc, v5
	v_mad_i32_i24 v50, v15, s0, 0
	v_mul_u32_u24_e32 v5, 0x104, v13
	v_and_b32_e32 v13, 48, v52
	v_or_b32_e32 v0, v37, v0
	v_mov_b32_e32 v169, v0
	v_lshl_add_u64 v[2:3], v[2:3], 1, v[10:11]
	v_mov_b32_e32 v167, v2
	v_mov_b32_e32 v168, v3
	v_add3_u32 v12, v50, v12, v5
	v_mul_u32_u24_e32 v10, 0x104, v13
	v_mul_hi_i32_i24_e32 v5, v4, v0
	v_mul_i32_i24_e32 v4, v4, v0
	v_ashrrev_i32_e32 v15, 31, v14
	v_lshlrev_b32_e32 v0, 1, v13
	v_add_u32_e32 v13, 0x1040, v12
	v_add3_u32 v50, v50, v10, v53
	v_lshl_add_u64 v[2:3], v[4:5], 1, v[2:3]
	v_add_u32_e32 v37, 0x1048, v12
	v_add_u32_e32 v51, 0x2080, v12
	v_add_u32_e32 v52, 0x2088, v12
	v_add_u32_e32 v54, 0x30c0, v12
	v_add_u32_e32 v55, 0x30c8, v12
	v_add_u32_e32 v53, 0x400, v50
	v_add_u32_e32 v56, 0x800, v50
	v_add_u32_e32 v57, 0xc00, v50
	v_lshl_add_u64 v[10:11], v[14:15], 1, v[2:3]
	v_lshl_add_u64 v[10:11], v[10:11], 0, v[0:1]
	v_lshlrev_b32_e32 v170, 1, v14
	v_add_u32_e32 v170, v170, v0
	v_lshrrev_b32_e32 v171, 4, v169
	v_mul_lo_u32 v171, v171, v173
	v_and_b32_e32 v172, 15, v169
	v_lshl_add_u32 v171, v172, 6, v171
	v_lshrrev_b32_e32 v172, 6, v170
	v_lshl_add_u32 v171, v172, 10, v171
	v_and_b32_e32 v172, 63, v170
	v_add_u32_e32 v171, v171, v172
	v_add_co_u32_e32 v167, vcc, v167, v171
	s_nop 1
	v_addc_co_u32_e32 v168, vcc, 0, v168, vcc
	v_cmp_eq_u32_e32 vcc, 1, v166
	s_nop 1
	v_cndmask_b32_e32 v10, v10, v167, vcc
	v_cndmask_b32_e32 v11, v11, v168, vcc
	s_waitcnt vmcnt(3)
	ds_write2_b32 v12, v6, v7 offset1:1
	ds_write2_b32 v12, v8, v9 offset0:2 offset1:3
	s_waitcnt vmcnt(2)
	ds_write2_b32 v13, v38, v39 offset1:1
	ds_write2_b32 v37, v40, v41 offset1:1
	s_waitcnt vmcnt(1)
	ds_write2_b32 v51, v42, v43 offset1:1
	ds_write2_b32 v52, v44, v45 offset1:1
	s_waitcnt vmcnt(0)
	ds_write2_b32 v54, v46, v47 offset1:1
	ds_write2_b32 v55, v48, v49 offset1:1
	s_waitcnt lgkmcnt(0)
	s_barrier
	ds_read2_b32 v[2:3], v50 offset1:65
	ds_read2_b32 v[4:5], v50 offset0:130 offset1:195
	ds_read2_b32 v[6:7], v53 offset0:4 offset1:69
	ds_read2_b32 v[8:9], v53 offset0:134 offset1:199
	ds_read2_b32 v[12:13], v56 offset0:8 offset1:73
	ds_read2_b32 v[14:15], v56 offset0:138 offset1:203
	ds_read2_b32 v[38:39], v57 offset0:12 offset1:77
	ds_read2_b32 v[40:41], v57 offset0:142 offset1:207
	s_waitcnt lgkmcnt(7)
	v_cvt_pk_bf16_f32 v2, v2, v3
	s_waitcnt lgkmcnt(6)
	v_cvt_pk_bf16_f32 v3, v4, v5
	s_waitcnt lgkmcnt(5)
	v_cvt_pk_bf16_f32 v4, v6, v7
	s_waitcnt lgkmcnt(4)
	v_cvt_pk_bf16_f32 v5, v8, v9
	s_waitcnt lgkmcnt(3)
	v_cvt_pk_bf16_f32 v6, v12, v13
	s_waitcnt lgkmcnt(2)
	v_cvt_pk_bf16_f32 v7, v14, v15
	s_waitcnt lgkmcnt(1)
	v_cvt_pk_bf16_f32 v8, v38, v39
	s_waitcnt lgkmcnt(0)
	v_cvt_pk_bf16_f32 v9, v40, v41
	global_store_dwordx4 v[10:11], v[2:5], off
	global_store_dwordx4 v[10:11], v[6:9], off offset:16
